# static priority raise for waves 4-7 also in the out-projection and w_o GEMM K-loops
# speedup vs baseline: 1.0022x; 1.0002x over previous
; #define PG8_STAGE(bufoff, gbase, voff) do { _Pragma("unroll") for (int _i = 0; _i < 2; ++_i) \
;         __builtin_amdgcn_global_load_lds((const unsigned*)((const char*)(gbase) + (voff)[_i]), (LAS unsigned*)(lds + (bufoff) + ldsw + _i * 8192), 16, 0, 0); } while (0)
; #define PG8_LDA(dst, b, h) do { _Pragma("unroll") for (int m = 0; m < 4; ++m) _Pragma("unroll") for (int k = 0; k < 2; ++k) dst[m][k] = *(const LAS bf16x8*)(lds + PG8_SA(b, h) + aoff + m * 2048 + k * 1024); } while (0)
; #define PG8_LDB(dst, b, h) do { _Pragma("unroll") for (int n = 0; n < 2; ++n) _Pragma("unroll") for (int k = 0; k < 2; ++k) dst[n][k] = *(const LAS bf16x8*)(lds + PG8_SB(b, h) + boff + n * 2048 + k * 1024); } while (0)
; #define PG8_MMA(ai, bj, At, Bt) do { __builtin_amdgcn_s_setprio(1); _Pragma("unroll") for (int m = 0; m < 4; ++m) _Pragma("unroll") for (int n = 0; n < 2; ++n) _Pragma("unroll") for (int k = 0; k < 2; ++k) \
;         acc[ai][bj][m][n] = __builtin_amdgcn_mfma_f32_16x16x32_bf16(Bt[n][k], At[m][k], acc[ai][bj][m][n], 0, 0, 0); __builtin_amdgcn_s_setprio(0); } while (0)
; #define PG8_WAIT_V(n) asm volatile("s_waitcnt vmcnt(" #n ")" ::: "memory")
; #define PG8_WAIT_L(n) asm volatile("s_waitcnt lgkmcnt(" #n ")" ::: "memory")
; template <class Epi, class Sched>
; __device__ __forceinline__ void gemm_phase(const int TID, LAS unsigned char* lds, const int lda, const int ldb, const Sched& S, const Epi& E) {
;     ...
;         for (int t = 0; t < nt; t += 2) {
;             const bool last = (t == nt - 2);
;             const char* a1 = cA + (size_t)(t + 1) * kstep;
;             const char* a2 = last ? nA : cA + (size_t)(t + 2) * kstep; const char* b2 = last ? nB : cB + (size_t)(t + 2) * kstep;
;             const char* a3 = a2 + kstep; const char* b3 = b2 + kstep;
;             PG8_LDB(B0, 0, 0); PG8_SCHED; PG8_LDA(At, 0, 0); PG8_STAGE(PG8_SA(1, 1), a1 + hA, voffA);
;             PG8_WAIT_L(8); PG8_BAR; PG8_WAIT_L(0); PG8_MMA(0, 0, At, B0); PG8_BAR; PG8_SCHED;
;             PG8_LDB(B1, 0, 1); PG8_STAGE(PG8_SB(0, 0), b2, voffB);
;             PG8_BAR; PG8_WAIT_L(0); PG8_MMA(0, 1, At, B1); PG8_BAR;
;             PG8_LDA(At, 0, 1); PG8_STAGE(PG8_SA(0, 0), a2, voffA);
;             PG8_BAR; PG8_WAIT_L(0); PG8_MMA(1, 0, At, B0); PG8_BAR; PG8_SCHED;
;             PG8_STAGE(PG8_SB(0, 1), b2 + hB, voffB);
;             PG8_WAIT_V(6); PG8_BAR; PG8_MMA(1, 1, At, B1); PG8_BAR;
.LBB0_27:
	s_cmpk_gt_u32 s21, 0xff
	s_cbranch_scc0 .Lk7_noprio
	s_setprio 1
.Lk7_noprio:
.Lk7_pbody:
	s_add_u32 s8, s50, 0xfff80080
	s_addc_u32 s9, s51, -1
	s_add_i32 s10, 0, 0x10000
	v_add_u32_e32 v158, s10, v155
	ds_read_b128 v[140:143], v158
	ds_read_b128 v[144:147], v158 offset:1024
	ds_read_b128 v[148:151], v158 offset:2048
	ds_read_b128 v[158:161], v158 offset:3072
	s_cmp_eq_u32 s49, 28
	s_cselect_b32 s55, s45, s9
	s_cselect_b32 s54, s44, s8
	s_cselect_b32 s53, s47, s43
	s_cselect_b32 s52, s46, s41
	v_lshl_add_u64 v[204:205], s[50:51], 0, v[138:139]
	s_add_i32 m0, s24, 0xc000
	ds_read_b128 v[162:165], v157
	ds_read_b128 v[166:169], v157 offset:1024
	ds_read_b128 v[170:173], v157 offset:2048
	ds_read_b128 v[174:177], v157 offset:3072
	ds_read_b128 v[178:181], v157 offset:4096
	ds_read_b128 v[186:189], v157 offset:5120
	ds_read_b128 v[196:199], v157 offset:6144
	ds_read_b128 v[200:203], v157 offset:7168
	global_load_lds_dwordx4 v[204:205], off
	v_lshl_add_u64 v[204:205], s[50:51], 0, v[136:137]
	s_add_i32 m0, s24, 0xe000
	s_nop 0
	global_load_lds_dwordx4 v[204:205], off
	s_waitcnt lgkmcnt(8)
	s_barrier
	s_waitcnt lgkmcnt(0)
	s_waitcnt lgkmcnt(0)
	v_mfma_f32_16x16x32_bf16 v[130:133], v[140:143], v[162:165], v[130:133]
	v_mfma_f32_16x16x32_bf16 v[126:129], v[148:151], v[162:165], v[126:129]
	v_mfma_f32_16x16x32_bf16 v[114:117], v[140:143], v[170:173], v[114:117]
	v_mfma_f32_16x16x32_bf16 v[110:113], v[148:151], v[170:173], v[110:113]
	v_mfma_f32_16x16x32_bf16 v[98:101], v[140:143], v[178:181], v[98:101]
	v_mfma_f32_16x16x32_bf16 v[94:97], v[148:151], v[178:181], v[94:97]
	v_mfma_f32_16x16x32_bf16 v[82:85], v[140:143], v[196:199], v[82:85]
	v_mfma_f32_16x16x32_bf16 v[78:81], v[148:151], v[196:199], v[78:81]
	v_mfma_f32_16x16x32_bf16 v[130:133], v[144:147], v[166:169], v[130:133]
	v_mfma_f32_16x16x32_bf16 v[126:129], v[158:161], v[166:169], v[126:129]
	v_mfma_f32_16x16x32_bf16 v[114:117], v[144:147], v[174:177], v[114:117]
	v_mfma_f32_16x16x32_bf16 v[110:113], v[158:161], v[174:177], v[110:113]
	v_mfma_f32_16x16x32_bf16 v[98:101], v[144:147], v[186:189], v[98:101]
	v_mfma_f32_16x16x32_bf16 v[94:97], v[158:161], v[186:189], v[94:97]
	v_mfma_f32_16x16x32_bf16 v[82:85], v[144:147], v[200:203], v[82:85]
	v_mfma_f32_16x16x32_bf16 v[78:81], v[158:161], v[200:203], v[78:81]
	s_barrier
	s_add_i32 s11, 0, 0x14000
	s_add_i32 s8, s10, s23
	v_add_u32_e32 v182, s11, v155
	v_lshl_add_u64 v[220:221], s[52:53], 0, v[12:13]
	s_mov_b32 m0, s8
	ds_read_b128 v[204:207], v182
	ds_read_b128 v[208:211], v182 offset:1024
	ds_read_b128 v[212:215], v182 offset:2048
	ds_read_b128 v[216:219], v182 offset:3072
	global_load_lds_dwordx4 v[220:221], off
	v_lshl_add_u64 v[222:223], s[52:53], 0, v[134:135]
	s_add_i32 m0, s8, 0x2000
	s_nop 0
	global_load_lds_dwordx4 v[222:223], off
	s_barrier
	s_waitcnt lgkmcnt(0)
	s_waitcnt lgkmcnt(0)
	v_mfma_f32_16x16x32_bf16 v[122:125], v[204:207], v[162:165], v[122:125]
	v_mfma_f32_16x16x32_bf16 v[118:121], v[212:215], v[162:165], v[118:121]
	v_mfma_f32_16x16x32_bf16 v[106:109], v[204:207], v[170:173], v[106:109]
	v_mfma_f32_16x16x32_bf16 v[102:105], v[212:215], v[170:173], v[102:105]
	v_mfma_f32_16x16x32_bf16 v[90:93], v[204:207], v[178:181], v[90:93]
	v_mfma_f32_16x16x32_bf16 v[86:89], v[212:215], v[178:181], v[86:89]
	v_mfma_f32_16x16x32_bf16 v[74:77], v[204:207], v[196:199], v[74:77]
	v_mfma_f32_16x16x32_bf16 v[70:73], v[212:215], v[196:199], v[70:73]
	v_mfma_f32_16x16x32_bf16 v[122:125], v[208:211], v[166:169], v[122:125]
	v_mfma_f32_16x16x32_bf16 v[118:121], v[216:219], v[166:169], v[118:121]
	v_mfma_f32_16x16x32_bf16 v[106:109], v[208:211], v[174:177], v[106:109]
	v_mfma_f32_16x16x32_bf16 v[102:105], v[216:219], v[174:177], v[102:105]
	v_mfma_f32_16x16x32_bf16 v[90:93], v[208:211], v[186:189], v[90:93]
	v_mfma_f32_16x16x32_bf16 v[86:89], v[216:219], v[186:189], v[86:89]
	v_mfma_f32_16x16x32_bf16 v[74:77], v[208:211], v[200:203], v[74:77]
	v_mfma_f32_16x16x32_bf16 v[70:73], v[216:219], v[200:203], v[70:73]
	s_mov_b32 m0, s24
	v_lshl_add_u64 v[236:237], s[54:55], 0, v[12:13]
	s_barrier
	ds_read_b128 v[162:165], v157 offset:16384
	ds_read_b128 v[166:169], v157 offset:17408
	ds_read_b128 v[170:173], v157 offset:18432
	ds_read_b128 v[174:177], v157 offset:19456
	ds_read_b128 v[178:181], v157 offset:20480
	ds_read_b128 v[186:189], v157 offset:21504
	ds_read_b128 v[196:199], v157 offset:22528
	ds_read_b128 v[200:203], v157 offset:23552
	global_load_lds_dwordx4 v[236:237], off
	v_lshl_add_u64 v[238:239], s[54:55], 0, v[134:135]
	s_mov_b32 m0, s56
	s_nop 0
	global_load_lds_dwordx4 v[238:239], off
	s_barrier
	s_waitcnt lgkmcnt(0)
	s_waitcnt lgkmcnt(0)
	v_mfma_f32_16x16x32_bf16 v[66:69], v[140:143], v[162:165], v[66:69]
	v_mfma_f32_16x16x32_bf16 v[62:65], v[148:151], v[162:165], v[62:65]
	v_mfma_f32_16x16x32_bf16 v[50:53], v[140:143], v[170:173], v[50:53]
	v_mfma_f32_16x16x32_bf16 v[46:49], v[148:151], v[170:173], v[46:49]
	v_mfma_f32_16x16x32_bf16 v[34:37], v[140:143], v[178:181], v[34:37]
	v_mfma_f32_16x16x32_bf16 v[30:33], v[148:151], v[178:181], v[30:33]
	v_mfma_f32_16x16x32_bf16 v[18:21], v[140:143], v[196:199], v[18:21]
	v_mfma_f32_16x16x32_bf16 v[8:11], v[148:151], v[196:199], v[8:11]
	v_mfma_f32_16x16x32_bf16 v[66:69], v[144:147], v[166:169], v[66:69]
	v_mfma_f32_16x16x32_bf16 v[62:65], v[158:161], v[166:169], v[62:65]
	v_mfma_f32_16x16x32_bf16 v[50:53], v[144:147], v[174:177], v[50:53]
	v_mfma_f32_16x16x32_bf16 v[46:49], v[158:161], v[174:177], v[46:49]
	v_mfma_f32_16x16x32_bf16 v[34:37], v[144:147], v[186:189], v[34:37]
	v_mfma_f32_16x16x32_bf16 v[30:33], v[158:161], v[186:189], v[30:33]
	v_mfma_f32_16x16x32_bf16 v[18:21], v[144:147], v[200:203], v[18:21]
	v_mfma_f32_16x16x32_bf16 v[8:11], v[158:161], v[200:203], v[8:11]
	s_barrier
; #define PG8_STAGE(bufoff, gbase, voff) do { _Pragma("unroll") for (int _i = 0; _i < 2; ++_i) \
;         __builtin_amdgcn_global_load_lds((const unsigned*)((const char*)(gbase) + (voff)[_i]), (LAS unsigned*)(lds + (bufoff) + ldsw + _i * 8192), 16, 0, 0); } while (0)
; #define PG8_LDA(dst, b, h) do { _Pragma("unroll") for (int m = 0; m < 4; ++m) _Pragma("unroll") for (int k = 0; k < 2; ++k) dst[m][k] = *(const LAS bf16x8*)(lds + PG8_SA(b, h) + aoff + m * 2048 + k * 1024); } while (0)
; #define PG8_LDB(dst, b, h) do { _Pragma("unroll") for (int n = 0; n < 2; ++n) _Pragma("unroll") for (int k = 0; k < 2; ++k) dst[n][k] = *(const LAS bf16x8*)(lds + PG8_SB(b, h) + boff + n * 2048 + k * 1024); } while (0)
; #define PG8_MMA(ai, bj, At, Bt) do { __builtin_amdgcn_s_setprio(1); _Pragma("unroll") for (int m = 0; m < 4; ++m) _Pragma("unroll") for (int n = 0; n < 2; ++n) _Pragma("unroll") for (int k = 0; k < 2; ++k) \
;         acc[ai][bj][m][n] = __builtin_amdgcn_mfma_f32_16x16x32_bf16(Bt[n][k], At[m][k], acc[ai][bj][m][n], 0, 0, 0); __builtin_amdgcn_s_setprio(0); } while (0)
; #define PG8_WAIT_V(n) asm volatile("s_waitcnt vmcnt(" #n ")" ::: "memory")
; #define PG8_WAIT_L(n) asm volatile("s_waitcnt lgkmcnt(" #n ")" ::: "memory")
; #define PG8_BAR __builtin_amdgcn_s_barrier()
; #define PG8_SCHED __builtin_amdgcn_sched_barrier(0)
; template <class Epi, class Sched>
; __device__ __forceinline__ void gemm_phase(const int TID, LAS unsigned char* lds, const int lda, const int ldb, const Sched& S, const Epi& E) {
;     ...
;             PG8_WAIT_V(6); PG8_BAR; PG8_MMA(1, 1, At, B1); PG8_BAR;
;             PG8_LDB(B0, 1, 0); PG8_SCHED; PG8_LDA(At, 1, 0); PG8_STAGE(PG8_SA(0, 1), a2 + hA, voffA);
;             PG8_WAIT_L(8); PG8_BAR; PG8_WAIT_L(0); PG8_MMA(0, 0, At, B0); PG8_BAR; PG8_SCHED;
;             PG8_LDB(B1, 1, 1); PG8_STAGE(PG8_SB(1, 0), b3, voffB);
;             PG8_BAR; PG8_WAIT_L(0); PG8_MMA(0, 1, At, B1); PG8_BAR;
;             PG8_LDA(At, 1, 1); PG8_STAGE(PG8_SA(1, 0), a3, voffA);
;             PG8_BAR; PG8_WAIT_L(0); PG8_MMA(1, 0, At, B0); PG8_BAR; PG8_SCHED;
	s_add_u32 s8, s52, 0x80000
	s_addc_u32 s9, s53, 0
	s_add_i32 s10, s11, s23
	v_lshl_add_u64 v[140:141], s[8:9], 0, v[12:13]
	s_mov_b32 m0, s10
	s_nop 0
	global_load_lds_dwordx4 v[140:141], off
	v_lshl_add_u64 v[140:141], s[8:9], 0, v[134:135]
	s_add_i32 m0, s10, 0x2000
	s_nop 0
	global_load_lds_dwordx4 v[140:141], off
	s_waitcnt vmcnt(6)
	s_barrier
	v_mfma_f32_16x16x32_bf16 v[58:61], v[204:207], v[162:165], v[58:61]
	v_mfma_f32_16x16x32_bf16 v[54:57], v[212:215], v[162:165], v[54:57]
	v_mfma_f32_16x16x32_bf16 v[42:45], v[204:207], v[170:173], v[42:45]
	v_mfma_f32_16x16x32_bf16 v[38:41], v[212:215], v[170:173], v[38:41]
	v_mfma_f32_16x16x32_bf16 v[26:29], v[204:207], v[178:181], v[26:29]
	v_mfma_f32_16x16x32_bf16 v[22:25], v[212:215], v[178:181], v[22:25]
	v_mfma_f32_16x16x32_bf16 v[4:7], v[204:207], v[196:199], v[4:7]
	v_mfma_f32_16x16x32_bf16 v[0:3], v[212:215], v[196:199], v[0:3]
	v_mfma_f32_16x16x32_bf16 v[58:61], v[208:211], v[166:169], v[58:61]
	v_mfma_f32_16x16x32_bf16 v[54:57], v[216:219], v[166:169], v[54:57]
	v_mfma_f32_16x16x32_bf16 v[42:45], v[208:211], v[174:177], v[42:45]
	v_mfma_f32_16x16x32_bf16 v[38:41], v[216:219], v[174:177], v[38:41]
	v_mfma_f32_16x16x32_bf16 v[26:29], v[208:211], v[186:189], v[26:29]
	v_mfma_f32_16x16x32_bf16 v[22:25], v[216:219], v[186:189], v[22:25]
	v_mfma_f32_16x16x32_bf16 v[4:7], v[208:211], v[200:203], v[4:7]
	v_mfma_f32_16x16x32_bf16 v[0:3], v[216:219], v[200:203], v[0:3]
	s_add_i32 s10, 0, 0x18000
	v_add_u32_e32 v158, s10, v155
	s_barrier
	ds_read_b128 v[140:143], v158
	ds_read_b128 v[144:147], v158 offset:1024
	ds_read_b128 v[148:151], v158 offset:2048
	ds_read_b128 v[158:161], v158 offset:3072
	s_add_u32 s8, s54, 0x80000
	s_addc_u32 s9, s55, 0
	s_mov_b32 m0, s57
	v_lshl_add_u64 v[204:205], s[8:9], 0, v[12:13]
	ds_read_b128 v[162:165], v157 offset:32768
	ds_read_b128 v[166:169], v157 offset:33792
	ds_read_b128 v[170:173], v157 offset:34816
	ds_read_b128 v[174:177], v157 offset:35840
	ds_read_b128 v[178:181], v157 offset:36864
	ds_read_b128 v[186:189], v157 offset:37888
	ds_read_b128 v[196:199], v157 offset:38912
	ds_read_b128 v[200:203], v157 offset:39936
	global_load_lds_dwordx4 v[204:205], off
	v_lshl_add_u64 v[204:205], s[8:9], 0, v[134:135]
	s_mov_b32 m0, s58
	s_nop 0
	global_load_lds_dwordx4 v[204:205], off
	s_waitcnt lgkmcnt(8)
	s_barrier
	s_waitcnt lgkmcnt(0)
	s_waitcnt lgkmcnt(0)
	v_mfma_f32_16x16x32_bf16 v[130:133], v[140:143], v[162:165], v[130:133]
	v_mfma_f32_16x16x32_bf16 v[126:129], v[148:151], v[162:165], v[126:129]
	v_mfma_f32_16x16x32_bf16 v[114:117], v[140:143], v[170:173], v[114:117]
	v_mfma_f32_16x16x32_bf16 v[110:113], v[148:151], v[170:173], v[110:113]
	v_mfma_f32_16x16x32_bf16 v[98:101], v[140:143], v[178:181], v[98:101]
	v_mfma_f32_16x16x32_bf16 v[94:97], v[148:151], v[178:181], v[94:97]
	v_mfma_f32_16x16x32_bf16 v[82:85], v[140:143], v[196:199], v[82:85]
	v_mfma_f32_16x16x32_bf16 v[78:81], v[148:151], v[196:199], v[78:81]
	v_mfma_f32_16x16x32_bf16 v[130:133], v[144:147], v[166:169], v[130:133]
	v_mfma_f32_16x16x32_bf16 v[126:129], v[158:161], v[166:169], v[126:129]
	v_mfma_f32_16x16x32_bf16 v[114:117], v[144:147], v[174:177], v[114:117]
	v_mfma_f32_16x16x32_bf16 v[110:113], v[158:161], v[174:177], v[110:113]
	v_mfma_f32_16x16x32_bf16 v[98:101], v[144:147], v[186:189], v[98:101]
	v_mfma_f32_16x16x32_bf16 v[94:97], v[158:161], v[186:189], v[94:97]
	v_mfma_f32_16x16x32_bf16 v[82:85], v[144:147], v[200:203], v[82:85]
	v_mfma_f32_16x16x32_bf16 v[78:81], v[158:161], v[200:203], v[78:81]
	s_barrier
	s_add_i32 s11, 0, 0x1c000
	s_add_i32 s8, s10, s23
	v_add_u32_e32 v182, s11, v155
	v_lshl_add_u64 v[220:221], v[220:221], 0, s[36:37]
	s_mov_b32 m0, s8
	ds_read_b128 v[204:207], v182
	ds_read_b128 v[208:211], v182 offset:1024
	ds_read_b128 v[212:215], v182 offset:2048
	ds_read_b128 v[216:219], v182 offset:3072
	global_load_lds_dwordx4 v[220:221], off
	v_lshl_add_u64 v[220:221], v[222:223], 0, s[36:37]
	s_add_i32 m0, s8, 0x2000
	s_nop 0
	global_load_lds_dwordx4 v[220:221], off
	s_barrier
	s_waitcnt lgkmcnt(0)
	s_waitcnt lgkmcnt(0)
	v_mfma_f32_16x16x32_bf16 v[122:125], v[204:207], v[162:165], v[122:125]
	v_mfma_f32_16x16x32_bf16 v[118:121], v[212:215], v[162:165], v[118:121]
	v_mfma_f32_16x16x32_bf16 v[106:109], v[204:207], v[170:173], v[106:109]
	v_mfma_f32_16x16x32_bf16 v[102:105], v[212:215], v[170:173], v[102:105]
	v_mfma_f32_16x16x32_bf16 v[90:93], v[204:207], v[178:181], v[90:93]
	v_mfma_f32_16x16x32_bf16 v[86:89], v[212:215], v[178:181], v[86:89]
	v_mfma_f32_16x16x32_bf16 v[74:77], v[204:207], v[196:199], v[74:77]
	v_mfma_f32_16x16x32_bf16 v[70:73], v[212:215], v[196:199], v[70:73]
	v_mfma_f32_16x16x32_bf16 v[122:125], v[208:211], v[166:169], v[122:125]
	v_mfma_f32_16x16x32_bf16 v[118:121], v[216:219], v[166:169], v[118:121]
	v_mfma_f32_16x16x32_bf16 v[106:109], v[208:211], v[174:177], v[106:109]
	v_mfma_f32_16x16x32_bf16 v[102:105], v[216:219], v[174:177], v[102:105]
	v_mfma_f32_16x16x32_bf16 v[90:93], v[208:211], v[186:189], v[90:93]
	v_mfma_f32_16x16x32_bf16 v[86:89], v[216:219], v[186:189], v[86:89]
	v_mfma_f32_16x16x32_bf16 v[74:77], v[208:211], v[200:203], v[74:77]
	v_mfma_f32_16x16x32_bf16 v[70:73], v[216:219], v[200:203], v[70:73]
	s_mov_b32 m0, s59
	v_lshl_add_u64 v[220:221], v[236:237], 0, s[36:37]
	s_barrier
	ds_read_b128 v[162:165], v157 offset:49152
	ds_read_b128 v[166:169], v157 offset:50176
	ds_read_b128 v[170:173], v157 offset:51200
	ds_read_b128 v[174:177], v157 offset:52224
	ds_read_b128 v[178:181], v157 offset:53248
	ds_read_b128 v[186:189], v157 offset:54272
	ds_read_b128 v[196:199], v157 offset:55296
	ds_read_b128 v[200:203], v157 offset:56320
	global_load_lds_dwordx4 v[220:221], off
	v_lshl_add_u64 v[220:221], v[238:239], 0, s[36:37]
	s_mov_b32 m0, s60
	s_nop 0
	global_load_lds_dwordx4 v[220:221], off
	s_barrier
; #define PG8_STAGE(bufoff, gbase, voff) do { _Pragma("unroll") for (int _i = 0; _i < 2; ++_i) \
;         __builtin_amdgcn_global_load_lds((const unsigned*)((const char*)(gbase) + (voff)[_i]), (LAS unsigned*)(lds + (bufoff) + ldsw + _i * 8192), 16, 0, 0); } while (0)
; #define PG8_MMA(ai, bj, At, Bt) do { __builtin_amdgcn_s_setprio(1); _Pragma("unroll") for (int m = 0; m < 4; ++m) _Pragma("unroll") for (int n = 0; n < 2; ++n) _Pragma("unroll") for (int k = 0; k < 2; ++k) \
;         acc[ai][bj][m][n] = __builtin_amdgcn_mfma_f32_16x16x32_bf16(Bt[n][k], At[m][k], acc[ai][bj][m][n], 0, 0, 0); __builtin_amdgcn_s_setprio(0); } while (0)
; #define PG8_WAIT_V(n) asm volatile("s_waitcnt vmcnt(" #n ")" ::: "memory")
; #define PG8_WAIT_L(n) asm volatile("s_waitcnt lgkmcnt(" #n ")" ::: "memory")
; #define PG8_BAR __builtin_amdgcn_s_barrier()
; #define PG8_SCHED __builtin_amdgcn_sched_barrier(0)
; template <class Epi, class Sched>
; __device__ __forceinline__ void gemm_phase(const int TID, LAS unsigned char* lds, const int lda, const int ldb, const Sched& S, const Epi& E) {
;     ...
;             PG8_BAR; PG8_WAIT_L(0); PG8_MMA(1, 0, At, B0); PG8_BAR; PG8_SCHED;
;             PG8_STAGE(PG8_SB(1, 1), b3 + hB, voffB);
;             PG8_WAIT_V(6); PG8_BAR; PG8_MMA(1, 1, At, B1); PG8_BAR;
; __device__ __forceinline__ const float* src_row(const Params& p, int r) {
;     int s, pos; if (r < 8224) { s = r / 4112; pos = r - s * 4112; } else { const int t = r - 8224; const int q = t / 2064; s = 2 + q; pos = t - q * 2064; }
;     if (pos < 16) return p.in[2] + (size_t)pos * D;
;     return s < 2 ? p.in[0] + ((size_t)s * 4096 + (pos - 16)) * D : p.in[1] + ((size_t)(s - 2) * 2048 + (pos - 16)) * D;
	s_waitcnt lgkmcnt(0)
	s_waitcnt lgkmcnt(0)
	v_mfma_f32_16x16x32_bf16 v[66:69], v[140:143], v[162:165], v[66:69]
	v_mfma_f32_16x16x32_bf16 v[62:65], v[148:151], v[162:165], v[62:65]
	v_mfma_f32_16x16x32_bf16 v[50:53], v[140:143], v[170:173], v[50:53]
	v_mfma_f32_16x16x32_bf16 v[46:49], v[148:151], v[170:173], v[46:49]
	v_mfma_f32_16x16x32_bf16 v[34:37], v[140:143], v[178:181], v[34:37]
	v_mfma_f32_16x16x32_bf16 v[30:33], v[148:151], v[178:181], v[30:33]
	v_mfma_f32_16x16x32_bf16 v[18:21], v[140:143], v[196:199], v[18:21]
	v_mfma_f32_16x16x32_bf16 v[8:11], v[148:151], v[196:199], v[8:11]
	v_mfma_f32_16x16x32_bf16 v[66:69], v[144:147], v[166:169], v[66:69]
	v_mfma_f32_16x16x32_bf16 v[62:65], v[158:161], v[166:169], v[62:65]
	v_mfma_f32_16x16x32_bf16 v[50:53], v[144:147], v[174:177], v[50:53]
	v_mfma_f32_16x16x32_bf16 v[46:49], v[158:161], v[174:177], v[46:49]
	v_mfma_f32_16x16x32_bf16 v[34:37], v[144:147], v[186:189], v[34:37]
	v_mfma_f32_16x16x32_bf16 v[30:33], v[158:161], v[186:189], v[30:33]
	v_mfma_f32_16x16x32_bf16 v[18:21], v[144:147], v[200:203], v[18:21]
	v_mfma_f32_16x16x32_bf16 v[8:11], v[158:161], v[200:203], v[8:11]
	s_barrier
	s_add_u32 s8, s52, 0x80080
	s_addc_u32 s9, s53, 0
	s_add_i32 s10, s11, s23
	v_lshl_add_u64 v[140:141], s[8:9], 0, v[12:13]
	s_mov_b32 m0, s10
	s_nop 0
	global_load_lds_dwordx4 v[140:141], off
	v_lshl_add_u64 v[140:141], s[8:9], 0, v[134:135]
	s_add_i32 m0, s10, 0x2000
	s_nop 0
	global_load_lds_dwordx4 v[140:141], off
	s_waitcnt vmcnt(6)
	s_barrier
	v_mfma_f32_16x16x32_bf16 v[58:61], v[204:207], v[162:165], v[58:61]
	v_mfma_f32_16x16x32_bf16 v[54:57], v[212:215], v[162:165], v[54:57]
	v_mfma_f32_16x16x32_bf16 v[42:45], v[204:207], v[170:173], v[42:45]
	v_mfma_f32_16x16x32_bf16 v[38:41], v[212:215], v[170:173], v[38:41]
	v_mfma_f32_16x16x32_bf16 v[26:29], v[204:207], v[178:181], v[26:29]
	v_mfma_f32_16x16x32_bf16 v[22:25], v[212:215], v[178:181], v[22:25]
	v_mfma_f32_16x16x32_bf16 v[4:7], v[204:207], v[196:199], v[4:7]
	v_mfma_f32_16x16x32_bf16 v[0:3], v[212:215], v[196:199], v[0:3]
	v_mfma_f32_16x16x32_bf16 v[58:61], v[208:211], v[166:169], v[58:61]
	v_mfma_f32_16x16x32_bf16 v[54:57], v[216:219], v[166:169], v[54:57]
	v_mfma_f32_16x16x32_bf16 v[42:45], v[208:211], v[174:177], v[42:45]
	v_mfma_f32_16x16x32_bf16 v[38:41], v[216:219], v[174:177], v[38:41]
	v_mfma_f32_16x16x32_bf16 v[26:29], v[208:211], v[186:189], v[26:29]
	v_mfma_f32_16x16x32_bf16 v[22:25], v[216:219], v[186:189], v[22:25]
	v_mfma_f32_16x16x32_bf16 v[4:7], v[208:211], v[200:203], v[4:7]
	v_mfma_f32_16x16x32_bf16 v[0:3], v[216:219], v[200:203], v[0:3]
	s_add_i32 s49, s49, 2
	s_add_u32 s41, s41, 0x100
	s_addc_u32 s43, s43, 0
	s_add_u32 s50, s50, 0x100
	s_addc_u32 s51, s51, 0
	s_cmp_gt_u32 s49, 29
	s_barrier
	s_cbranch_scc0 .Lk7_pbody
	s_setprio 0
	v_lshl_add_u32 v142, s48, 8, v154
	v_lshl_or_b32 v140, s63, 8, v156
	s_movk_i32 s8, 0x60a0
	v_ashrrev_i32_e32 v141, 31, v140
	v_cmp_gt_i32_e32 vcc, s8, v142
	s_and_saveexec_b64 s[48:49], vcc
	s_cbranch_execz .LBB0_44
	v_ashrrev_i32_e32 v143, 31, v142
	v_lshlrev_b64 v[144:145], 13, v[142:143]
	v_lshl_add_u64 v[144:145], s[94:95], 0, v[144:145]
	s_andn2_b64 vcc, exec, s[28:29]
	v_mov_b64_e32 v[146:147], v[144:145]
	s_cbranch_vccnz .LBB0_43
	s_movk_i32 s8, 0x201f
	v_cmp_lt_i32_e32 vcc, s8, v142
	s_and_saveexec_b64 s[8:9], vcc
	s_xor_b64 s[50:51], exec, s[8:9]
	v_add_u32_e32 v143, 0xffffdfe0, v142
	v_mul_u32_u24_e32 v146, 0x3f81, v143
	v_lshrrev_b32_e32 v146, 25, v146
	s_movk_i32 s8, 0xf7f0
	v_add_u32_e32 v148, 2, v146
	v_mad_i32_i24 v146, v146, s8, v143
	s_andn2_saveexec_b64 s[50:51], s[50:51]
	s_mov_b32 s8, 0x7f807f81
	v_mul_hi_i32 v143, v142, s8
	v_lshrrev_b32_e32 v146, 31, v143
	v_ashrrev_i32_e32 v143, 11, v143
	v_add_u32_e32 v148, v143, v146
	s_movk_i32 s8, 0xeff0
	v_mad_i32_i24 v146, v148, s8, v142
	s_or_b64 exec, exec, s[50:51]
	v_readlane_b32 s64, v254, 0
	v_readlane_b32 s68, v254, 4
	v_readlane_b32 s69, v254, 5
	v_cmp_lt_i32_e32 vcc, 15, v146
	v_readlane_b32 s65, v254, 1
	v_mov_b64_e32 v[150:151], s[68:69]
	v_readlane_b32 s66, v254, 2
	v_readlane_b32 s67, v254, 3
	v_readlane_b32 s70, v254, 6
	v_readlane_b32 s71, v254, 7
	v_readlane_b32 s72, v254, 8
	v_readlane_b32 s73, v254, 9
	v_readlane_b32 s74, v254, 10
	v_readlane_b32 s75, v254, 11
	v_readlane_b32 s76, v254, 12
	v_readlane_b32 s77, v254, 13
	v_readlane_b32 s78, v254, 14
	v_readlane_b32 s79, v254, 15
	s_and_saveexec_b64 s[8:9], vcc
	s_xor_b64 s[50:51], exec, s[8:9]
	s_cbranch_execz .LBB0_40
	v_cmp_lt_i32_e32 vcc, 1, v148
	v_add_u32_e32 v182, -16, v146
	s_and_saveexec_b64 s[8:9], vcc
	s_xor_b64 s[52:53], exec, s[8:9]
	s_cbranch_execz .LBB0_37
	v_add_u32_e32 v146, -2, v148
	v_mov_b32_e32 v147, v183
	v_readlane_b32 s64, v254, 0
	v_lshlrev_b64 v[146:147], 24, v[146:147]
	v_readlane_b32 s66, v254, 2
	v_readlane_b32 s67, v254, 3
	v_readlane_b32 s65, v254, 1
	v_readlane_b32 s68, v254, 4
	v_readlane_b32 s69, v254, 5
	v_readlane_b32 s70, v254, 6
	v_readlane_b32 s71, v254, 7
	v_readlane_b32 s72, v254, 8
	v_readlane_b32 s73, v254, 9
	v_readlane_b32 s74, v254, 10
	v_readlane_b32 s75, v254, 11
	v_readlane_b32 s76, v254, 12
	v_readlane_b32 s77, v254, 13
	v_readlane_b32 s78, v254, 14
	v_readlane_b32 s79, v254, 15
	v_lshl_add_u64 v[150:151], s[66:67], 0, v[146:147]
	v_mov_b64_e32 v[146:147], v[182:183]

; #define PG8_STAGE(bufoff, gbase, voff) do { _Pragma("unroll") for (int _i = 0; _i < 2; ++_i) \
;         __builtin_amdgcn_global_load_lds((const unsigned*)((const char*)(gbase) + (voff)[_i]), (LAS unsigned*)(lds + (bufoff) + ldsw + _i * 8192), 16, 0, 0); } while (0)
; #define PG8_LDA(dst, b, h) do { _Pragma("unroll") for (int m = 0; m < 4; ++m) _Pragma("unroll") for (int k = 0; k < 2; ++k) dst[m][k] = *(const LAS bf16x8*)(lds + PG8_SA(b, h) + aoff + m * 2048 + k * 1024); } while (0)
; #define PG8_LDB(dst, b, h) do { _Pragma("unroll") for (int n = 0; n < 2; ++n) _Pragma("unroll") for (int k = 0; k < 2; ++k) dst[n][k] = *(const LAS bf16x8*)(lds + PG8_SB(b, h) + boff + n * 2048 + k * 1024); } while (0)
; #define PG8_MMA(ai, bj, At, Bt) do { __builtin_amdgcn_s_setprio(1); _Pragma("unroll") for (int m = 0; m < 4; ++m) _Pragma("unroll") for (int n = 0; n < 2; ++n) _Pragma("unroll") for (int k = 0; k < 2; ++k) \
;         acc[ai][bj][m][n] = __builtin_amdgcn_mfma_f32_16x16x32_bf16(Bt[n][k], At[m][k], acc[ai][bj][m][n], 0, 0, 0); __builtin_amdgcn_s_setprio(0); } while (0)
; #define PG8_WAIT_V(n) asm volatile("s_waitcnt vmcnt(" #n ")" ::: "memory")
; #define PG8_WAIT_L(n) asm volatile("s_waitcnt lgkmcnt(" #n ")" ::: "memory")
; template <class Epi, class Sched>
; __device__ __forceinline__ void gemm_phase(const int TID, LAS unsigned char* lds, const int lda, const int ldb, const Sched& S, const Epi& E) {
;     ...
;         for (int t = 0; t < nt; t += 2) {
;             const bool last = (t == nt - 2);
;             const char* a1 = cA + (size_t)(t + 1) * kstep;
;             const char* a2 = last ? nA : cA + (size_t)(t + 2) * kstep; const char* b2 = last ? nB : cB + (size_t)(t + 2) * kstep;
;             const char* a3 = a2 + kstep; const char* b3 = b2 + kstep;
;             PG8_LDB(B0, 0, 0); PG8_SCHED; PG8_LDA(At, 0, 0); PG8_STAGE(PG8_SA(1, 1), a1 + hA, voffA);
;             PG8_WAIT_L(8); PG8_BAR; PG8_WAIT_L(0); PG8_MMA(0, 0, At, B0); PG8_BAR; PG8_SCHED;
;             PG8_LDB(B1, 0, 1); PG8_STAGE(PG8_SB(0, 0), b2, voffB);
;             PG8_BAR; PG8_WAIT_L(0); PG8_MMA(0, 1, At, B1); PG8_BAR;
;             PG8_LDA(At, 0, 1); PG8_STAGE(PG8_SA(0, 0), a2, voffA);
;             PG8_BAR; PG8_WAIT_L(0); PG8_MMA(1, 0, At, B0); PG8_BAR; PG8_SCHED;
;             PG8_STAGE(PG8_SB(0, 1), b2 + hB, voffB);
;             PG8_WAIT_V(6); PG8_BAR; PG8_MMA(1, 1, At, B1); PG8_BAR;
.Lk6_nozero:
.LBB0_236:
	s_cmpk_gt_u32 s21, 0xff
	s_cbranch_scc0 .Lk6_noprio
	s_setprio 1
.Lk6_noprio:
.Lk6_pbody:
	s_add_i32 s70, s54, 2
	s_add_u32 s8, s52, 0xfff80080
	s_addc_u32 s9, s53, -1
	s_add_i32 s10, 0, 0x10000
	v_add_u32_e32 v146, s10, v238
	ds_read_b128 v[106:109], v146
	ds_read_b128 v[118:121], v146 offset:1024
	ds_read_b128 v[134:137], v146 offset:2048
	ds_read_b128 v[146:149], v146 offset:3072
	s_cmp_eq_u32 s45, s54
	s_cselect_b32 s54, s50, s47
	s_cselect_b32 s57, s49, s9
	s_cselect_b32 s56, s48, s8
	s_cselect_b32 s55, s51, s69
	v_lshl_add_u64 v[186:187], s[52:53], 0, v[204:205]
	s_add_i32 m0, s24, 0xc000
	ds_read_b128 v[150:153], v240
	ds_read_b128 v[154:157], v240 offset:1024
	ds_read_b128 v[158:161], v240 offset:2048
	ds_read_b128 v[162:165], v240 offset:3072
	ds_read_b128 v[166:169], v240 offset:4096
	ds_read_b128 v[170:173], v240 offset:5120
	ds_read_b128 v[174:177], v240 offset:6144
	ds_read_b128 v[178:181], v240 offset:7168
	global_load_lds_dwordx4 v[186:187], off
	v_lshl_add_u64 v[186:187], s[52:53], 0, v[202:203]
	s_add_i32 m0, s24, 0xe000
	s_nop 0
	global_load_lds_dwordx4 v[186:187], off
	s_waitcnt lgkmcnt(8)
	s_barrier
	s_waitcnt lgkmcnt(0)
	s_waitcnt lgkmcnt(0)
	v_mfma_f32_16x16x32_bf16 v[142:145], v[106:109], v[150:153], v[142:145]
	v_mfma_f32_16x16x32_bf16 v[138:141], v[134:137], v[150:153], v[138:141]
	v_mfma_f32_16x16x32_bf16 v[122:125], v[106:109], v[158:161], v[122:125]
	v_mfma_f32_16x16x32_bf16 v[114:117], v[134:137], v[158:161], v[114:117]
	v_mfma_f32_16x16x32_bf16 v[98:101], v[106:109], v[166:169], v[98:101]
	v_mfma_f32_16x16x32_bf16 v[94:97], v[134:137], v[166:169], v[94:97]
	v_mfma_f32_16x16x32_bf16 v[82:85], v[106:109], v[174:177], v[82:85]
	v_mfma_f32_16x16x32_bf16 v[78:81], v[134:137], v[174:177], v[78:81]
	v_mfma_f32_16x16x32_bf16 v[142:145], v[118:121], v[154:157], v[142:145]
	v_mfma_f32_16x16x32_bf16 v[138:141], v[146:149], v[154:157], v[138:141]
	v_mfma_f32_16x16x32_bf16 v[122:125], v[118:121], v[162:165], v[122:125]
	v_mfma_f32_16x16x32_bf16 v[114:117], v[146:149], v[162:165], v[114:117]
	v_mfma_f32_16x16x32_bf16 v[98:101], v[118:121], v[170:173], v[98:101]
	v_mfma_f32_16x16x32_bf16 v[94:97], v[146:149], v[170:173], v[94:97]
	v_mfma_f32_16x16x32_bf16 v[82:85], v[118:121], v[178:181], v[82:85]
	v_mfma_f32_16x16x32_bf16 v[78:81], v[146:149], v[178:181], v[78:81]
	s_barrier
	s_add_i32 s11, 0, 0x14000
	s_add_i32 s8, s10, s23
	v_add_u32_e32 v214, s11, v238
	v_lshl_add_u64 v[218:219], s[54:55], 0, v[182:183]
	s_mov_b32 m0, s8
	ds_read_b128 v[186:189], v214
	ds_read_b128 v[206:209], v214 offset:1024
	ds_read_b128 v[210:213], v214 offset:2048
	ds_read_b128 v[214:217], v214 offset:3072
	global_load_lds_dwordx4 v[218:219], off
	v_lshl_add_u64 v[220:221], s[54:55], 0, v[198:199]
	s_add_i32 m0, s8, 0x2000
	s_nop 0
	global_load_lds_dwordx4 v[220:221], off
	s_barrier
	s_waitcnt lgkmcnt(0)
	s_waitcnt lgkmcnt(0)
	v_mfma_f32_16x16x32_bf16 v[130:133], v[186:189], v[150:153], v[130:133]
	v_mfma_f32_16x16x32_bf16 v[126:129], v[210:213], v[150:153], v[126:129]
	v_mfma_f32_16x16x32_bf16 v[110:113], v[186:189], v[158:161], v[110:113]
	v_mfma_f32_16x16x32_bf16 v[102:105], v[210:213], v[158:161], v[102:105]
	v_mfma_f32_16x16x32_bf16 v[90:93], v[186:189], v[166:169], v[90:93]
	v_mfma_f32_16x16x32_bf16 v[86:89], v[210:213], v[166:169], v[86:89]
	v_mfma_f32_16x16x32_bf16 v[74:77], v[186:189], v[174:177], v[74:77]
	v_mfma_f32_16x16x32_bf16 v[70:73], v[210:213], v[174:177], v[70:73]
	v_mfma_f32_16x16x32_bf16 v[130:133], v[206:209], v[154:157], v[130:133]
	v_mfma_f32_16x16x32_bf16 v[126:129], v[214:217], v[154:157], v[126:129]
	v_mfma_f32_16x16x32_bf16 v[110:113], v[206:209], v[162:165], v[110:113]
	v_mfma_f32_16x16x32_bf16 v[102:105], v[214:217], v[162:165], v[102:105]
	v_mfma_f32_16x16x32_bf16 v[90:93], v[206:209], v[170:173], v[90:93]
	v_mfma_f32_16x16x32_bf16 v[86:89], v[214:217], v[170:173], v[86:89]
	v_mfma_f32_16x16x32_bf16 v[74:77], v[206:209], v[178:181], v[74:77]
	v_mfma_f32_16x16x32_bf16 v[70:73], v[214:217], v[178:181], v[70:73]
	s_mov_b32 m0, s24
	v_lshl_add_u64 v[222:223], s[56:57], 0, v[12:13]
	s_barrier
	ds_read_b128 v[150:153], v240 offset:16384
	ds_read_b128 v[154:157], v240 offset:17408
	ds_read_b128 v[158:161], v240 offset:18432
	ds_read_b128 v[162:165], v240 offset:19456
	ds_read_b128 v[166:169], v240 offset:20480
	ds_read_b128 v[170:173], v240 offset:21504
	ds_read_b128 v[174:177], v240 offset:22528
	ds_read_b128 v[178:181], v240 offset:23552
	global_load_lds_dwordx4 v[222:223], off
	v_lshl_add_u64 v[242:243], s[56:57], 0, v[196:197]
	s_mov_b32 m0, s58
	s_nop 0
	global_load_lds_dwordx4 v[242:243], off
	s_barrier
	s_waitcnt lgkmcnt(0)
	s_waitcnt lgkmcnt(0)
	v_mfma_f32_16x16x32_bf16 v[66:69], v[106:109], v[150:153], v[66:69]
	v_mfma_f32_16x16x32_bf16 v[62:65], v[134:137], v[150:153], v[62:65]
	v_mfma_f32_16x16x32_bf16 v[50:53], v[106:109], v[158:161], v[50:53]
	v_mfma_f32_16x16x32_bf16 v[46:49], v[134:137], v[158:161], v[46:49]
	v_mfma_f32_16x16x32_bf16 v[34:37], v[106:109], v[166:169], v[34:37]
	v_mfma_f32_16x16x32_bf16 v[30:33], v[134:137], v[166:169], v[30:33]
	v_mfma_f32_16x16x32_bf16 v[18:21], v[106:109], v[174:177], v[18:21]
	v_mfma_f32_16x16x32_bf16 v[8:11], v[134:137], v[174:177], v[8:11]
	v_mfma_f32_16x16x32_bf16 v[66:69], v[118:121], v[154:157], v[66:69]
	v_mfma_f32_16x16x32_bf16 v[62:65], v[146:149], v[154:157], v[62:65]
	v_mfma_f32_16x16x32_bf16 v[50:53], v[118:121], v[162:165], v[50:53]
	v_mfma_f32_16x16x32_bf16 v[46:49], v[146:149], v[162:165], v[46:49]
	v_mfma_f32_16x16x32_bf16 v[34:37], v[118:121], v[170:173], v[34:37]
	v_mfma_f32_16x16x32_bf16 v[30:33], v[146:149], v[170:173], v[30:33]
	v_mfma_f32_16x16x32_bf16 v[18:21], v[118:121], v[178:181], v[18:21]
	v_mfma_f32_16x16x32_bf16 v[8:11], v[146:149], v[178:181], v[8:11]
	s_barrier
; #define PG8_STAGE(bufoff, gbase, voff) do { _Pragma("unroll") for (int _i = 0; _i < 2; ++_i) \
;         __builtin_amdgcn_global_load_lds((const unsigned*)((const char*)(gbase) + (voff)[_i]), (LAS unsigned*)(lds + (bufoff) + ldsw + _i * 8192), 16, 0, 0); } while (0)
; #define PG8_LDA(dst, b, h) do { _Pragma("unroll") for (int m = 0; m < 4; ++m) _Pragma("unroll") for (int k = 0; k < 2; ++k) dst[m][k] = *(const LAS bf16x8*)(lds + PG8_SA(b, h) + aoff + m * 2048 + k * 1024); } while (0)
; #define PG8_LDB(dst, b, h) do { _Pragma("unroll") for (int n = 0; n < 2; ++n) _Pragma("unroll") for (int k = 0; k < 2; ++k) dst[n][k] = *(const LAS bf16x8*)(lds + PG8_SB(b, h) + boff + n * 2048 + k * 1024); } while (0)
; #define PG8_MMA(ai, bj, At, Bt) do { __builtin_amdgcn_s_setprio(1); _Pragma("unroll") for (int m = 0; m < 4; ++m) _Pragma("unroll") for (int n = 0; n < 2; ++n) _Pragma("unroll") for (int k = 0; k < 2; ++k) \
;         acc[ai][bj][m][n] = __builtin_amdgcn_mfma_f32_16x16x32_bf16(Bt[n][k], At[m][k], acc[ai][bj][m][n], 0, 0, 0); __builtin_amdgcn_s_setprio(0); } while (0)
; #define PG8_WAIT_V(n) asm volatile("s_waitcnt vmcnt(" #n ")" ::: "memory")
; #define PG8_WAIT_L(n) asm volatile("s_waitcnt lgkmcnt(" #n ")" ::: "memory")
; #define PG8_BAR __builtin_amdgcn_s_barrier()
; #define PG8_SCHED __builtin_amdgcn_sched_barrier(0)
; template <class Epi, class Sched>
; __device__ __forceinline__ void gemm_phase(const int TID, LAS unsigned char* lds, const int lda, const int ldb, const Sched& S, const Epi& E) {
;     ...
;             PG8_WAIT_V(6); PG8_BAR; PG8_MMA(1, 1, At, B1); PG8_BAR;
;             PG8_LDB(B0, 1, 0); PG8_SCHED; PG8_LDA(At, 1, 0); PG8_STAGE(PG8_SA(0, 1), a2 + hA, voffA);
;             PG8_WAIT_L(8); PG8_BAR; PG8_WAIT_L(0); PG8_MMA(0, 0, At, B0); PG8_BAR; PG8_SCHED;
;             PG8_LDB(B1, 1, 1); PG8_STAGE(PG8_SB(1, 0), b3, voffB);
;             PG8_BAR; PG8_WAIT_L(0); PG8_MMA(0, 1, At, B1); PG8_BAR;
;             PG8_LDA(At, 1, 1); PG8_STAGE(PG8_SA(1, 0), a3, voffA);
;             PG8_BAR; PG8_WAIT_L(0); PG8_MMA(1, 0, At, B0); PG8_BAR; PG8_SCHED;
	s_add_u32 s8, s54, 0x80000
	s_addc_u32 s9, s55, 0
	s_add_i32 s10, s11, s23
	v_lshl_add_u64 v[106:107], s[8:9], 0, v[182:183]
	s_mov_b32 m0, s10
	s_nop 0
	global_load_lds_dwordx4 v[106:107], off
	v_lshl_add_u64 v[106:107], s[8:9], 0, v[198:199]
	s_add_i32 m0, s10, 0x2000
	s_nop 0
	global_load_lds_dwordx4 v[106:107], off
	s_waitcnt vmcnt(6)
	s_barrier
	v_mfma_f32_16x16x32_bf16 v[58:61], v[186:189], v[150:153], v[58:61]
	v_mfma_f32_16x16x32_bf16 v[54:57], v[210:213], v[150:153], v[54:57]
	v_mfma_f32_16x16x32_bf16 v[42:45], v[186:189], v[158:161], v[42:45]
	v_mfma_f32_16x16x32_bf16 v[38:41], v[210:213], v[158:161], v[38:41]
	v_mfma_f32_16x16x32_bf16 v[26:29], v[186:189], v[166:169], v[26:29]
	v_mfma_f32_16x16x32_bf16 v[22:25], v[210:213], v[166:169], v[22:25]
	v_mfma_f32_16x16x32_bf16 v[4:7], v[186:189], v[174:177], v[4:7]
	v_mfma_f32_16x16x32_bf16 v[0:3], v[210:213], v[174:177], v[0:3]
	v_mfma_f32_16x16x32_bf16 v[58:61], v[206:209], v[154:157], v[58:61]
	v_mfma_f32_16x16x32_bf16 v[54:57], v[214:217], v[154:157], v[54:57]
	v_mfma_f32_16x16x32_bf16 v[42:45], v[206:209], v[162:165], v[42:45]
	v_mfma_f32_16x16x32_bf16 v[38:41], v[214:217], v[162:165], v[38:41]
	v_mfma_f32_16x16x32_bf16 v[26:29], v[206:209], v[170:173], v[26:29]
	v_mfma_f32_16x16x32_bf16 v[22:25], v[214:217], v[170:173], v[22:25]
	v_mfma_f32_16x16x32_bf16 v[4:7], v[206:209], v[178:181], v[4:7]
	v_mfma_f32_16x16x32_bf16 v[0:3], v[214:217], v[178:181], v[0:3]
	s_add_i32 s10, 0, 0x18000
	v_add_u32_e32 v146, s10, v238
	s_barrier
	ds_read_b128 v[106:109], v146
	ds_read_b128 v[118:121], v146 offset:1024
	ds_read_b128 v[134:137], v146 offset:2048
	ds_read_b128 v[146:149], v146 offset:3072
	s_add_u32 s8, s56, 0x80000
	s_addc_u32 s9, s57, 0
	s_mov_b32 m0, s59
	v_lshl_add_u64 v[186:187], s[8:9], 0, v[12:13]
	ds_read_b128 v[150:153], v240 offset:32768
	ds_read_b128 v[154:157], v240 offset:33792
	ds_read_b128 v[158:161], v240 offset:34816
	ds_read_b128 v[162:165], v240 offset:35840
	ds_read_b128 v[166:169], v240 offset:36864
	ds_read_b128 v[170:173], v240 offset:37888
	ds_read_b128 v[174:177], v240 offset:38912
	ds_read_b128 v[178:181], v240 offset:39936
	global_load_lds_dwordx4 v[186:187], off
	v_lshl_add_u64 v[186:187], s[8:9], 0, v[196:197]
	s_mov_b32 m0, s60
	s_nop 0
	global_load_lds_dwordx4 v[186:187], off
	s_waitcnt lgkmcnt(8)
	s_barrier
	s_waitcnt lgkmcnt(0)
	s_waitcnt lgkmcnt(0)
	v_mfma_f32_16x16x32_bf16 v[142:145], v[106:109], v[150:153], v[142:145]
	v_mfma_f32_16x16x32_bf16 v[138:141], v[134:137], v[150:153], v[138:141]
	v_mfma_f32_16x16x32_bf16 v[122:125], v[106:109], v[158:161], v[122:125]
	v_mfma_f32_16x16x32_bf16 v[114:117], v[134:137], v[158:161], v[114:117]
	v_mfma_f32_16x16x32_bf16 v[98:101], v[106:109], v[166:169], v[98:101]
	v_mfma_f32_16x16x32_bf16 v[94:97], v[134:137], v[166:169], v[94:97]
	v_mfma_f32_16x16x32_bf16 v[82:85], v[106:109], v[174:177], v[82:85]
	v_mfma_f32_16x16x32_bf16 v[78:81], v[134:137], v[174:177], v[78:81]
	v_mfma_f32_16x16x32_bf16 v[142:145], v[118:121], v[154:157], v[142:145]
	v_mfma_f32_16x16x32_bf16 v[138:141], v[146:149], v[154:157], v[138:141]
	v_mfma_f32_16x16x32_bf16 v[122:125], v[118:121], v[162:165], v[122:125]
	v_mfma_f32_16x16x32_bf16 v[114:117], v[146:149], v[162:165], v[114:117]
	v_mfma_f32_16x16x32_bf16 v[98:101], v[118:121], v[170:173], v[98:101]
	v_mfma_f32_16x16x32_bf16 v[94:97], v[146:149], v[170:173], v[94:97]
	v_mfma_f32_16x16x32_bf16 v[82:85], v[118:121], v[178:181], v[82:85]
	v_mfma_f32_16x16x32_bf16 v[78:81], v[146:149], v[178:181], v[78:81]
	s_barrier
	s_add_i32 s11, 0, 0x1c000
	s_add_i32 s8, s10, s23
	v_add_u32_e32 v214, s11, v238
	v_lshl_add_u64 v[218:219], v[218:219], 0, s[36:37]
	s_mov_b32 m0, s8
	ds_read_b128 v[186:189], v214
	ds_read_b128 v[206:209], v214 offset:1024
	ds_read_b128 v[210:213], v214 offset:2048
	ds_read_b128 v[214:217], v214 offset:3072
	global_load_lds_dwordx4 v[218:219], off
	v_lshl_add_u64 v[218:219], v[220:221], 0, s[36:37]
	s_add_i32 m0, s8, 0x2000
	s_nop 0
	global_load_lds_dwordx4 v[218:219], off
	s_barrier
	s_waitcnt lgkmcnt(0)
	s_waitcnt lgkmcnt(0)
	v_mfma_f32_16x16x32_bf16 v[130:133], v[186:189], v[150:153], v[130:133]
	v_mfma_f32_16x16x32_bf16 v[126:129], v[210:213], v[150:153], v[126:129]
	v_mfma_f32_16x16x32_bf16 v[110:113], v[186:189], v[158:161], v[110:113]
	v_mfma_f32_16x16x32_bf16 v[102:105], v[210:213], v[158:161], v[102:105]
	v_mfma_f32_16x16x32_bf16 v[90:93], v[186:189], v[166:169], v[90:93]
	v_mfma_f32_16x16x32_bf16 v[86:89], v[210:213], v[166:169], v[86:89]
	v_mfma_f32_16x16x32_bf16 v[74:77], v[186:189], v[174:177], v[74:77]
	v_mfma_f32_16x16x32_bf16 v[70:73], v[210:213], v[174:177], v[70:73]
	v_mfma_f32_16x16x32_bf16 v[130:133], v[206:209], v[154:157], v[130:133]
	v_mfma_f32_16x16x32_bf16 v[126:129], v[214:217], v[154:157], v[126:129]
	v_mfma_f32_16x16x32_bf16 v[110:113], v[206:209], v[162:165], v[110:113]
	v_mfma_f32_16x16x32_bf16 v[102:105], v[214:217], v[162:165], v[102:105]
	v_mfma_f32_16x16x32_bf16 v[90:93], v[206:209], v[170:173], v[90:93]
	v_mfma_f32_16x16x32_bf16 v[86:89], v[214:217], v[170:173], v[86:89]
	v_mfma_f32_16x16x32_bf16 v[74:77], v[206:209], v[178:181], v[74:77]
	v_mfma_f32_16x16x32_bf16 v[70:73], v[214:217], v[178:181], v[70:73]
	s_mov_b32 m0, s61
	v_lshl_add_u64 v[218:219], v[222:223], 0, s[36:37]
	s_barrier
	ds_read_b128 v[150:153], v240 offset:49152
	ds_read_b128 v[154:157], v240 offset:50176
	ds_read_b128 v[158:161], v240 offset:51200
	ds_read_b128 v[162:165], v240 offset:52224
	ds_read_b128 v[166:169], v240 offset:53248
	ds_read_b128 v[170:173], v240 offset:54272
	ds_read_b128 v[174:177], v240 offset:55296
	ds_read_b128 v[178:181], v240 offset:56320
	global_load_lds_dwordx4 v[218:219], off
	v_lshl_add_u64 v[218:219], v[242:243], 0, s[36:37]
	s_mov_b32 m0, s62
	s_nop 0
	global_load_lds_dwordx4 v[218:219], off
	s_barrier
; #define PG8_STAGE(bufoff, gbase, voff) do { _Pragma("unroll") for (int _i = 0; _i < 2; ++_i) \
;         __builtin_amdgcn_global_load_lds((const unsigned*)((const char*)(gbase) + (voff)[_i]), (LAS unsigned*)(lds + (bufoff) + ldsw + _i * 8192), 16, 0, 0); } while (0)
; #define PG8_MMA(ai, bj, At, Bt) do { __builtin_amdgcn_s_setprio(1); _Pragma("unroll") for (int m = 0; m < 4; ++m) _Pragma("unroll") for (int n = 0; n < 2; ++n) _Pragma("unroll") for (int k = 0; k < 2; ++k) \
;         acc[ai][bj][m][n] = __builtin_amdgcn_mfma_f32_16x16x32_bf16(Bt[n][k], At[m][k], acc[ai][bj][m][n], 0, 0, 0); __builtin_amdgcn_s_setprio(0); } while (0)
; #define PG8_WAIT_V(n) asm volatile("s_waitcnt vmcnt(" #n ")" ::: "memory")
; #define PG8_WAIT_L(n) asm volatile("s_waitcnt lgkmcnt(" #n ")" ::: "memory")
; #define PG8_BAR __builtin_amdgcn_s_barrier()
; #define PG8_SCHED __builtin_amdgcn_sched_barrier(0)
; template <class Epi, class Sched>
; __device__ __forceinline__ void gemm_phase(const int TID, LAS unsigned char* lds, const int lda, const int ldb, const Sched& S, const Epi& E) {
;     ...
;             PG8_BAR; PG8_WAIT_L(0); PG8_MMA(1, 0, At, B0); PG8_BAR; PG8_SCHED;
;             PG8_STAGE(PG8_SB(1, 1), b3 + hB, voffB);
;             PG8_WAIT_V(6); PG8_BAR; PG8_MMA(1, 1, At, B1); PG8_BAR;
	s_waitcnt lgkmcnt(0)
	s_waitcnt lgkmcnt(0)
	v_mfma_f32_16x16x32_bf16 v[66:69], v[106:109], v[150:153], v[66:69]
	v_mfma_f32_16x16x32_bf16 v[62:65], v[134:137], v[150:153], v[62:65]
	v_mfma_f32_16x16x32_bf16 v[50:53], v[106:109], v[158:161], v[50:53]
	v_mfma_f32_16x16x32_bf16 v[46:49], v[134:137], v[158:161], v[46:49]
	v_mfma_f32_16x16x32_bf16 v[34:37], v[106:109], v[166:169], v[34:37]
	v_mfma_f32_16x16x32_bf16 v[30:33], v[134:137], v[166:169], v[30:33]
	v_mfma_f32_16x16x32_bf16 v[18:21], v[106:109], v[174:177], v[18:21]
	v_mfma_f32_16x16x32_bf16 v[8:11], v[134:137], v[174:177], v[8:11]
	v_mfma_f32_16x16x32_bf16 v[66:69], v[118:121], v[154:157], v[66:69]
	v_mfma_f32_16x16x32_bf16 v[62:65], v[146:149], v[154:157], v[62:65]
	v_mfma_f32_16x16x32_bf16 v[50:53], v[118:121], v[162:165], v[50:53]
	v_mfma_f32_16x16x32_bf16 v[46:49], v[146:149], v[162:165], v[46:49]
	v_mfma_f32_16x16x32_bf16 v[34:37], v[118:121], v[170:173], v[34:37]
	v_mfma_f32_16x16x32_bf16 v[30:33], v[146:149], v[170:173], v[30:33]
	v_mfma_f32_16x16x32_bf16 v[18:21], v[118:121], v[178:181], v[18:21]
	v_mfma_f32_16x16x32_bf16 v[8:11], v[146:149], v[178:181], v[8:11]
	s_barrier
	s_add_u32 s8, s54, 0x80080
	s_addc_u32 s9, s55, 0
	s_add_i32 s10, s11, s23
	v_lshl_add_u64 v[106:107], s[8:9], 0, v[182:183]
	s_mov_b32 m0, s10
	s_nop 0
	global_load_lds_dwordx4 v[106:107], off
	v_lshl_add_u64 v[106:107], s[8:9], 0, v[198:199]
	s_add_i32 m0, s10, 0x2000
	s_nop 0
	global_load_lds_dwordx4 v[106:107], off
	s_waitcnt vmcnt(6)
	s_barrier
	v_mfma_f32_16x16x32_bf16 v[58:61], v[186:189], v[150:153], v[58:61]
	v_mfma_f32_16x16x32_bf16 v[54:57], v[210:213], v[150:153], v[54:57]
	v_mfma_f32_16x16x32_bf16 v[42:45], v[186:189], v[158:161], v[42:45]
	v_mfma_f32_16x16x32_bf16 v[38:41], v[210:213], v[158:161], v[38:41]
	v_mfma_f32_16x16x32_bf16 v[26:29], v[186:189], v[166:169], v[26:29]
	v_mfma_f32_16x16x32_bf16 v[22:25], v[210:213], v[166:169], v[22:25]
	v_mfma_f32_16x16x32_bf16 v[4:7], v[186:189], v[174:177], v[4:7]
	v_mfma_f32_16x16x32_bf16 v[0:3], v[210:213], v[174:177], v[0:3]
	v_mfma_f32_16x16x32_bf16 v[58:61], v[206:209], v[154:157], v[58:61]
	v_mfma_f32_16x16x32_bf16 v[54:57], v[214:217], v[154:157], v[54:57]
	v_mfma_f32_16x16x32_bf16 v[42:45], v[206:209], v[162:165], v[42:45]
	v_mfma_f32_16x16x32_bf16 v[38:41], v[214:217], v[162:165], v[38:41]
	v_mfma_f32_16x16x32_bf16 v[26:29], v[206:209], v[170:173], v[26:29]
	v_mfma_f32_16x16x32_bf16 v[22:25], v[214:217], v[170:173], v[22:25]
	v_mfma_f32_16x16x32_bf16 v[4:7], v[206:209], v[178:181], v[4:7]
	v_mfma_f32_16x16x32_bf16 v[0:3], v[214:217], v[178:181], v[0:3]
	s_add_u32 s47, s47, 0x100
	s_addc_u32 s69, s69, 0
	s_add_u32 s52, s52, 0x100
	s_addc_u32 s53, s53, 0
	s_cmp_ge_i32 s70, s68
	s_mov_b32 s54, s70
	s_barrier
	s_cbranch_scc0 .Lk6_pbody
	s_setprio 0
	s_cmp_eq_u32 s41, 2
	s_cbranch_scc1 .Lk6_final
	v_lshl_add_u32 v206, s40, 8, v237
	s_lshl_b32 s8, s41, 11
	s_lshl_b32 s9, s67, 8
	s_add_i32 s8, s8, s9
	s_addk_i32 s8, 0x2400
	s_add_u32 s10, s42, s8
	s_addc_u32 s11, s43, 0
	v_mad_u32_u24 v206, v206, s4, v200
	s_mov_b32 s9, 0x2f800000
	global_load_dwordx4 v[150:153], v206, s[10:11]
	global_load_dwordx4 v[106:109], v206, s[10:11] offset:2048
	s_add_u32 s10, s10, 0x56000
	s_addc_u32 s11, s11, 0
	global_load_dwordx4 v[154:157], v206, s[10:11]
	global_load_dwordx4 v[118:121], v206, s[10:11] offset:2048
	s_add_u32 s10, s10, 0x56000
	s_addc_u32 s11, s11, 0
	global_load_dwordx4 v[158:161], v206, s[10:11]
	global_load_dwordx4 v[134:137], v206, s[10:11] offset:2048
	s_add_u32 s10, s10, 0x56000
	s_addc_u32 s11, s11, 0
	global_load_dwordx4 v[162:165], v206, s[10:11]
	global_load_dwordx4 v[146:149], v206, s[10:11] offset:2048
	s_add_u32 s10, s10, 0x1ae000
	s_addc_u32 s11, s11, 0
	global_load_dwordx4 v[166:169], v206, s[10:11]
	global_load_dwordx4 v[186:189], v206, s[10:11] offset:2048
	s_add_u32 s10, s10, 0x56000
	s_addc_u32 s11, s11, 0
	global_load_dwordx4 v[170:173], v206, s[10:11]
	global_load_dwordx4 v[208:211], v206, s[10:11] offset:2048
	s_add_u32 s10, s10, 0x56000
	s_addc_u32 s11, s11, 0
	global_load_dwordx4 v[174:177], v206, s[10:11]
	global_load_dwordx4 v[212:215], v206, s[10:11] offset:2048
	s_add_u32 s10, s10, 0x56000
	s_addc_u32 s11, s11, 0
	global_load_dwordx4 v[178:181], v206, s[10:11]
	global_load_dwordx4 v[216:219], v206, s[10:11] offset:2048
	s_waitcnt vmcnt(14)
	v_cvt_f32_ubyte0_e32 v206, v106
	v_cvt_f32_ubyte1_e32 v207, v106
	v_cvt_f32_ubyte2_e32 v220, v106
	v_cvt_f32_ubyte3_e32 v221, v106
	v_cvt_f32_ubyte0_e32 v222, v150
	v_cvt_f32_ubyte1_e32 v223, v150
	v_cvt_f32_ubyte2_e32 v242, v150
	v_cvt_f32_ubyte3_e32 v243, v150
	v_max_f32_e32 v206, s9, v206
	v_max_f32_e32 v207, s9, v207
	v_max_f32_e32 v220, s9, v220
	v_max_f32_e32 v221, s9, v221
	v_max_f32_e32 v222, s9, v222
	v_max_f32_e32 v223, s9, v223
	v_max_f32_e32 v242, s9, v242
	v_max_f32_e32 v243, s9, v243
	v_rcp_f32_e32 v206, v206
	v_rcp_f32_e32 v207, v207
	v_rcp_f32_e32 v220, v220
	v_rcp_f32_e32 v221, v221
	v_mul_f32_e32 v222, v206, v222
	v_mul_f32_e32 v223, v207, v223
	v_mul_f32_e32 v242, v220, v242
	v_mul_f32_e32 v243, v221, v243
	v_mul_f32_e32 v142, v222, v142
	v_mul_f32_e32 v143, v223, v143
	v_mul_f32_e32 v144, v242, v144
	v_mul_f32_e32 v145, v243, v145
	v_cvt_f32_ubyte0_e32 v206, v107
	v_cvt_f32_ubyte1_e32 v207, v107
	v_cvt_f32_ubyte2_e32 v220, v107
	v_cvt_f32_ubyte3_e32 v221, v107
	v_cvt_f32_ubyte0_e32 v222, v151
	v_cvt_f32_ubyte1_e32 v223, v151
	v_cvt_f32_ubyte2_e32 v242, v151
	v_cvt_f32_ubyte3_e32 v243, v151
	v_max_f32_e32 v206, s9, v206
	v_max_f32_e32 v207, s9, v207
	v_max_f32_e32 v220, s9, v220
	v_max_f32_e32 v221, s9, v221
	v_max_f32_e32 v222, s9, v222
	v_max_f32_e32 v223, s9, v223
	v_max_f32_e32 v242, s9, v242
	v_max_f32_e32 v243, s9, v243
	v_rcp_f32_e32 v206, v206
	v_rcp_f32_e32 v207, v207
	v_rcp_f32_e32 v220, v220
	v_rcp_f32_e32 v221, v221
	v_mul_f32_e32 v222, v206, v222
	v_mul_f32_e32 v223, v207, v223
	v_mul_f32_e32 v242, v220, v242
	v_mul_f32_e32 v243, v221, v243
	v_mul_f32_e32 v138, v222, v138
	v_mul_f32_e32 v139, v223, v139
	v_mul_f32_e32 v140, v242, v140
	v_mul_f32_e32 v141, v243, v141
	v_cvt_f32_ubyte0_e32 v206, v108
	v_cvt_f32_ubyte1_e32 v207, v108
	v_cvt_f32_ubyte2_e32 v220, v108
	v_cvt_f32_ubyte3_e32 v221, v108
	v_cvt_f32_ubyte0_e32 v222, v152
	v_cvt_f32_ubyte1_e32 v223, v152
	v_cvt_f32_ubyte2_e32 v242, v152
	v_cvt_f32_ubyte3_e32 v243, v152
	v_max_f32_e32 v206, s9, v206
	v_max_f32_e32 v207, s9, v207
	v_max_f32_e32 v220, s9, v220
	v_max_f32_e32 v221, s9, v221
	v_max_f32_e32 v222, s9, v222
	v_max_f32_e32 v223, s9, v223
	v_max_f32_e32 v242, s9, v242
	v_max_f32_e32 v243, s9, v243
	v_rcp_f32_e32 v206, v206
	v_rcp_f32_e32 v207, v207
	v_rcp_f32_e32 v220, v220
	v_rcp_f32_e32 v221, v221
	v_mul_f32_e32 v222, v206, v222
	v_mul_f32_e32 v223, v207, v223
	v_mul_f32_e32 v242, v220, v242
	v_mul_f32_e32 v243, v221, v243
	v_mul_f32_e32 v130, v222, v130
	v_mul_f32_e32 v131, v223, v131
	v_mul_f32_e32 v132, v242, v132
	v_mul_f32_e32 v133, v243, v133
	v_cvt_f32_ubyte0_e32 v206, v109
	v_cvt_f32_ubyte1_e32 v207, v109
	v_cvt_f32_ubyte2_e32 v220, v109
	v_cvt_f32_ubyte3_e32 v221, v109
	v_cvt_f32_ubyte0_e32 v222, v153
	v_cvt_f32_ubyte1_e32 v223, v153
	v_cvt_f32_ubyte2_e32 v242, v153
	v_cvt_f32_ubyte3_e32 v243, v153
	v_max_f32_e32 v206, s9, v206
	v_max_f32_e32 v207, s9, v207
	v_max_f32_e32 v220, s9, v220
	v_max_f32_e32 v221, s9, v221
	v_max_f32_e32 v222, s9, v222
	v_max_f32_e32 v223, s9, v223
	v_max_f32_e32 v242, s9, v242
	v_max_f32_e32 v243, s9, v243
	v_rcp_f32_e32 v206, v206
	v_rcp_f32_e32 v207, v207
	v_rcp_f32_e32 v220, v220
	v_rcp_f32_e32 v221, v221
	v_mul_f32_e32 v222, v206, v222
	v_mul_f32_e32 v223, v207, v223
	v_mul_f32_e32 v242, v220, v242
	v_mul_f32_e32 v243, v221, v243
	v_mul_f32_e32 v126, v222, v126
	v_mul_f32_e32 v127, v223, v127
	v_mul_f32_e32 v128, v242, v128
	v_mul_f32_e32 v129, v243, v129
	s_waitcnt vmcnt(12)
	v_cvt_f32_ubyte0_e32 v206, v118
	v_cvt_f32_ubyte1_e32 v207, v118
	v_cvt_f32_ubyte2_e32 v220, v118
	v_cvt_f32_ubyte3_e32 v221, v118
	v_cvt_f32_ubyte0_e32 v222, v154
	v_cvt_f32_ubyte1_e32 v223, v154
	v_cvt_f32_ubyte2_e32 v242, v154
	v_cvt_f32_ubyte3_e32 v243, v154
	v_max_f32_e32 v206, s9, v206
	v_max_f32_e32 v207, s9, v207
	v_max_f32_e32 v220, s9, v220
	v_max_f32_e32 v221, s9, v221
	v_max_f32_e32 v222, s9, v222
	v_max_f32_e32 v223, s9, v223
	v_max_f32_e32 v242, s9, v242
	v_max_f32_e32 v243, s9, v243
	v_rcp_f32_e32 v206, v206
	v_rcp_f32_e32 v207, v207
	v_rcp_f32_e32 v220, v220
	v_rcp_f32_e32 v221, v221
	v_mul_f32_e32 v222, v206, v222
	v_mul_f32_e32 v223, v207, v223
	v_mul_f32_e32 v242, v220, v242
	v_mul_f32_e32 v243, v221, v243
	v_mul_f32_e32 v122, v222, v122
	v_mul_f32_e32 v123, v223, v123
	v_mul_f32_e32 v124, v242, v124
	v_mul_f32_e32 v125, v243, v125
	v_cvt_f32_ubyte0_e32 v206, v119
	v_cvt_f32_ubyte1_e32 v207, v119
	v_cvt_f32_ubyte2_e32 v220, v119
	v_cvt_f32_ubyte3_e32 v221, v119
	v_cvt_f32_ubyte0_e32 v222, v155
	v_cvt_f32_ubyte1_e32 v223, v155
	v_cvt_f32_ubyte2_e32 v242, v155
	v_cvt_f32_ubyte3_e32 v243, v155
	v_max_f32_e32 v206, s9, v206
	v_max_f32_e32 v207, s9, v207
	v_max_f32_e32 v220, s9, v220
	v_max_f32_e32 v221, s9, v221
	v_max_f32_e32 v222, s9, v222
	v_max_f32_e32 v223, s9, v223
	v_max_f32_e32 v242, s9, v242
	v_max_f32_e32 v243, s9, v243
	v_rcp_f32_e32 v206, v206
	v_rcp_f32_e32 v207, v207
	v_rcp_f32_e32 v220, v220
	v_rcp_f32_e32 v221, v221
	v_mul_f32_e32 v222, v206, v222
	v_mul_f32_e32 v223, v207, v223
	v_mul_f32_e32 v242, v220, v242
	v_mul_f32_e32 v243, v221, v243
	v_mul_f32_e32 v114, v222, v114
	v_mul_f32_e32 v115, v223, v115
	v_mul_f32_e32 v116, v242, v116
	v_mul_f32_e32 v117, v243, v117
	v_cvt_f32_ubyte0_e32 v206, v120
	v_cvt_f32_ubyte1_e32 v207, v120
	v_cvt_f32_ubyte2_e32 v220, v120
	v_cvt_f32_ubyte3_e32 v221, v120
	v_cvt_f32_ubyte0_e32 v222, v156
	v_cvt_f32_ubyte1_e32 v223, v156
	v_cvt_f32_ubyte2_e32 v242, v156
	v_cvt_f32_ubyte3_e32 v243, v156
	v_max_f32_e32 v206, s9, v206
	v_max_f32_e32 v207, s9, v207
	v_max_f32_e32 v220, s9, v220
	v_max_f32_e32 v221, s9, v221
	v_max_f32_e32 v222, s9, v222
	v_max_f32_e32 v223, s9, v223
	v_max_f32_e32 v242, s9, v242
	v_max_f32_e32 v243, s9, v243
	v_rcp_f32_e32 v206, v206
	v_rcp_f32_e32 v207, v207
	v_rcp_f32_e32 v220, v220
	v_rcp_f32_e32 v221, v221
	v_mul_f32_e32 v222, v206, v222
	v_mul_f32_e32 v223, v207, v223
	v_mul_f32_e32 v242, v220, v242
	v_mul_f32_e32 v243, v221, v243
	v_mul_f32_e32 v110, v222, v110
	v_mul_f32_e32 v111, v223, v111
	v_mul_f32_e32 v112, v242, v112
	v_mul_f32_e32 v113, v243, v113
	v_cvt_f32_ubyte0_e32 v206, v121
	v_cvt_f32_ubyte1_e32 v207, v121
	v_cvt_f32_ubyte2_e32 v220, v121
	v_cvt_f32_ubyte3_e32 v221, v121
	v_cvt_f32_ubyte0_e32 v222, v157
	v_cvt_f32_ubyte1_e32 v223, v157
	v_cvt_f32_ubyte2_e32 v242, v157
	v_cvt_f32_ubyte3_e32 v243, v157
	v_max_f32_e32 v206, s9, v206
	v_max_f32_e32 v207, s9, v207
	v_max_f32_e32 v220, s9, v220
	v_max_f32_e32 v221, s9, v221
	v_max_f32_e32 v222, s9, v222
	v_max_f32_e32 v223, s9, v223
	v_max_f32_e32 v242, s9, v242
	v_max_f32_e32 v243, s9, v243
	v_rcp_f32_e32 v206, v206
	v_rcp_f32_e32 v207, v207
	v_rcp_f32_e32 v220, v220
	v_rcp_f32_e32 v221, v221
	v_mul_f32_e32 v222, v206, v222
	v_mul_f32_e32 v223, v207, v223
	v_mul_f32_e32 v242, v220, v242
	v_mul_f32_e32 v243, v221, v243
	v_mul_f32_e32 v102, v222, v102
	v_mul_f32_e32 v103, v223, v103
	v_mul_f32_e32 v104, v242, v104
	v_mul_f32_e32 v105, v243, v105
	s_waitcnt vmcnt(10)
	v_cvt_f32_ubyte0_e32 v206, v134
	v_cvt_f32_ubyte1_e32 v207, v134
	v_cvt_f32_ubyte2_e32 v220, v134
	v_cvt_f32_ubyte3_e32 v221, v134
	v_cvt_f32_ubyte0_e32 v222, v158
	v_cvt_f32_ubyte1_e32 v223, v158
	v_cvt_f32_ubyte2_e32 v242, v158
	v_cvt_f32_ubyte3_e32 v243, v158
	v_max_f32_e32 v206, s9, v206
	v_max_f32_e32 v207, s9, v207
	v_max_f32_e32 v220, s9, v220
	v_max_f32_e32 v221, s9, v221
	v_max_f32_e32 v222, s9, v222
	v_max_f32_e32 v223, s9, v223
	v_max_f32_e32 v242, s9, v242
	v_max_f32_e32 v243, s9, v243
	v_rcp_f32_e32 v206, v206
	v_rcp_f32_e32 v207, v207
	v_rcp_f32_e32 v220, v220
	v_rcp_f32_e32 v221, v221
	v_mul_f32_e32 v222, v206, v222
	v_mul_f32_e32 v223, v207, v223
	v_mul_f32_e32 v242, v220, v242
	v_mul_f32_e32 v243, v221, v243
	v_mul_f32_e32 v98, v222, v98
	v_mul_f32_e32 v99, v223, v99
	v_mul_f32_e32 v100, v242, v100
	v_mul_f32_e32 v101, v243, v101
	v_cvt_f32_ubyte0_e32 v206, v135
	v_cvt_f32_ubyte1_e32 v207, v135
	v_cvt_f32_ubyte2_e32 v220, v135
	v_cvt_f32_ubyte3_e32 v221, v135
	v_cvt_f32_ubyte0_e32 v222, v159
	v_cvt_f32_ubyte1_e32 v223, v159
	v_cvt_f32_ubyte2_e32 v242, v159
	v_cvt_f32_ubyte3_e32 v243, v159
	v_max_f32_e32 v206, s9, v206
	v_max_f32_e32 v207, s9, v207
	v_max_f32_e32 v220, s9, v220
	v_max_f32_e32 v221, s9, v221
	v_max_f32_e32 v222, s9, v222
	v_max_f32_e32 v223, s9, v223
	v_max_f32_e32 v242, s9, v242
	v_max_f32_e32 v243, s9, v243
	v_rcp_f32_e32 v206, v206
	v_rcp_f32_e32 v207, v207
	v_rcp_f32_e32 v220, v220
	v_rcp_f32_e32 v221, v221
	v_mul_f32_e32 v222, v206, v222
	v_mul_f32_e32 v223, v207, v223
	v_mul_f32_e32 v242, v220, v242
	v_mul_f32_e32 v243, v221, v243
	v_mul_f32_e32 v94, v222, v94
	v_mul_f32_e32 v95, v223, v95
	v_mul_f32_e32 v96, v242, v96
	v_mul_f32_e32 v97, v243, v97
	v_cvt_f32_ubyte0_e32 v206, v136
	v_cvt_f32_ubyte1_e32 v207, v136
	v_cvt_f32_ubyte2_e32 v220, v136
	v_cvt_f32_ubyte3_e32 v221, v136
	v_cvt_f32_ubyte0_e32 v222, v160
	v_cvt_f32_ubyte1_e32 v223, v160
	v_cvt_f32_ubyte2_e32 v242, v160
	v_cvt_f32_ubyte3_e32 v243, v160
	v_max_f32_e32 v206, s9, v206
	v_max_f32_e32 v207, s9, v207
	v_max_f32_e32 v220, s9, v220
	v_max_f32_e32 v221, s9, v221
	v_max_f32_e32 v222, s9, v222
	v_max_f32_e32 v223, s9, v223
	v_max_f32_e32 v242, s9, v242
	v_max_f32_e32 v243, s9, v243
	v_rcp_f32_e32 v206, v206
	v_rcp_f32_e32 v207, v207
	v_rcp_f32_e32 v220, v220
	v_rcp_f32_e32 v221, v221
	v_mul_f32_e32 v222, v206, v222
	v_mul_f32_e32 v223, v207, v223
	v_mul_f32_e32 v242, v220, v242
	v_mul_f32_e32 v243, v221, v243
	v_mul_f32_e32 v90, v222, v90
	v_mul_f32_e32 v91, v223, v91
	v_mul_f32_e32 v92, v242, v92
	v_mul_f32_e32 v93, v243, v93
	v_cvt_f32_ubyte0_e32 v206, v137
	v_cvt_f32_ubyte1_e32 v207, v137
	v_cvt_f32_ubyte2_e32 v220, v137
	v_cvt_f32_ubyte3_e32 v221, v137
	v_cvt_f32_ubyte0_e32 v222, v161
	v_cvt_f32_ubyte1_e32 v223, v161
	v_cvt_f32_ubyte2_e32 v242, v161
	v_cvt_f32_ubyte3_e32 v243, v161
	v_max_f32_e32 v206, s9, v206
	v_max_f32_e32 v207, s9, v207
	v_max_f32_e32 v220, s9, v220
	v_max_f32_e32 v221, s9, v221
	v_max_f32_e32 v222, s9, v222
	v_max_f32_e32 v223, s9, v223
	v_max_f32_e32 v242, s9, v242
	v_max_f32_e32 v243, s9, v243
	v_rcp_f32_e32 v206, v206
	v_rcp_f32_e32 v207, v207
	v_rcp_f32_e32 v220, v220
	v_rcp_f32_e32 v221, v221
	v_mul_f32_e32 v222, v206, v222
	v_mul_f32_e32 v223, v207, v223
	v_mul_f32_e32 v242, v220, v242
	v_mul_f32_e32 v243, v221, v243
	v_mul_f32_e32 v86, v222, v86
	v_mul_f32_e32 v87, v223, v87
	v_mul_f32_e32 v88, v242, v88
	v_mul_f32_e32 v89, v243, v89
	s_waitcnt vmcnt(8)
	v_cvt_f32_ubyte0_e32 v206, v146
	v_cvt_f32_ubyte1_e32 v207, v146
	v_cvt_f32_ubyte2_e32 v220, v146
	v_cvt_f32_ubyte3_e32 v221, v146
	v_cvt_f32_ubyte0_e32 v222, v162
	v_cvt_f32_ubyte1_e32 v223, v162
	v_cvt_f32_ubyte2_e32 v242, v162
	v_cvt_f32_ubyte3_e32 v243, v162
	v_max_f32_e32 v206, s9, v206
	v_max_f32_e32 v207, s9, v207
	v_max_f32_e32 v220, s9, v220
	v_max_f32_e32 v221, s9, v221
	v_max_f32_e32 v222, s9, v222
	v_max_f32_e32 v223, s9, v223
	v_max_f32_e32 v242, s9, v242
	v_max_f32_e32 v243, s9, v243
	v_rcp_f32_e32 v206, v206
	v_rcp_f32_e32 v207, v207
	v_rcp_f32_e32 v220, v220
	v_rcp_f32_e32 v221, v221
	v_mul_f32_e32 v222, v206, v222
	v_mul_f32_e32 v223, v207, v223
	v_mul_f32_e32 v242, v220, v242
	v_mul_f32_e32 v243, v221, v243
	v_mul_f32_e32 v82, v222, v82
	v_mul_f32_e32 v83, v223, v83
	v_mul_f32_e32 v84, v242, v84
	v_mul_f32_e32 v85, v243, v85
	v_cvt_f32_ubyte0_e32 v206, v147
	v_cvt_f32_ubyte1_e32 v207, v147
	v_cvt_f32_ubyte2_e32 v220, v147
	v_cvt_f32_ubyte3_e32 v221, v147
	v_cvt_f32_ubyte0_e32 v222, v163
	v_cvt_f32_ubyte1_e32 v223, v163
	v_cvt_f32_ubyte2_e32 v242, v163
	v_cvt_f32_ubyte3_e32 v243, v163
	v_max_f32_e32 v206, s9, v206
	v_max_f32_e32 v207, s9, v207
	v_max_f32_e32 v220, s9, v220
	v_max_f32_e32 v221, s9, v221
	v_max_f32_e32 v222, s9, v222
	v_max_f32_e32 v223, s9, v223
	v_max_f32_e32 v242, s9, v242
	v_max_f32_e32 v243, s9, v243
	v_rcp_f32_e32 v206, v206
	v_rcp_f32_e32 v207, v207
	v_rcp_f32_e32 v220, v220
	v_rcp_f32_e32 v221, v221
	v_mul_f32_e32 v222, v206, v222
	v_mul_f32_e32 v223, v207, v223
	v_mul_f32_e32 v242, v220, v242
	v_mul_f32_e32 v243, v221, v243
	v_mul_f32_e32 v78, v222, v78
	v_mul_f32_e32 v79, v223, v79
	v_mul_f32_e32 v80, v242, v80
	v_mul_f32_e32 v81, v243, v81
	v_cvt_f32_ubyte0_e32 v206, v148
	v_cvt_f32_ubyte1_e32 v207, v148
	v_cvt_f32_ubyte2_e32 v220, v148
	v_cvt_f32_ubyte3_e32 v221, v148
	v_cvt_f32_ubyte0_e32 v222, v164
	v_cvt_f32_ubyte1_e32 v223, v164
	v_cvt_f32_ubyte2_e32 v242, v164
	v_cvt_f32_ubyte3_e32 v243, v164
	v_max_f32_e32 v206, s9, v206
	v_max_f32_e32 v207, s9, v207
	v_max_f32_e32 v220, s9, v220
	v_max_f32_e32 v221, s9, v221
	v_max_f32_e32 v222, s9, v222
	v_max_f32_e32 v223, s9, v223
	v_max_f32_e32 v242, s9, v242
	v_max_f32_e32 v243, s9, v243
	v_rcp_f32_e32 v206, v206
	v_rcp_f32_e32 v207, v207
	v_rcp_f32_e32 v220, v220
	v_rcp_f32_e32 v221, v221
	v_mul_f32_e32 v222, v206, v222
	v_mul_f32_e32 v223, v207, v223
	v_mul_f32_e32 v242, v220, v242
	v_mul_f32_e32 v243, v221, v243
	v_mul_f32_e32 v74, v222, v74
	v_mul_f32_e32 v75, v223, v75
	v_mul_f32_e32 v76, v242, v76
	v_mul_f32_e32 v77, v243, v77
	v_cvt_f32_ubyte0_e32 v206, v149
	v_cvt_f32_ubyte1_e32 v207, v149
	v_cvt_f32_ubyte2_e32 v220, v149
	v_cvt_f32_ubyte3_e32 v221, v149
	v_cvt_f32_ubyte0_e32 v222, v165
	v_cvt_f32_ubyte1_e32 v223, v165
	v_cvt_f32_ubyte2_e32 v242, v165
	v_cvt_f32_ubyte3_e32 v243, v165
	v_max_f32_e32 v206, s9, v206
	v_max_f32_e32 v207, s9, v207
	v_max_f32_e32 v220, s9, v220
	v_max_f32_e32 v221, s9, v221
	v_max_f32_e32 v222, s9, v222
	v_max_f32_e32 v223, s9, v223
	v_max_f32_e32 v242, s9, v242
	v_max_f32_e32 v243, s9, v243
	v_rcp_f32_e32 v206, v206
	v_rcp_f32_e32 v207, v207
	v_rcp_f32_e32 v220, v220
	v_rcp_f32_e32 v221, v221
	v_mul_f32_e32 v222, v206, v222
	v_mul_f32_e32 v223, v207, v223
	v_mul_f32_e32 v242, v220, v242
	v_mul_f32_e32 v243, v221, v243
	v_mul_f32_e32 v70, v222, v70
	v_mul_f32_e32 v71, v223, v71
	v_mul_f32_e32 v72, v242, v72
	v_mul_f32_e32 v73, v243, v73
	s_waitcnt vmcnt(6)
	v_cvt_f32_ubyte0_e32 v206, v186
	v_cvt_f32_ubyte1_e32 v207, v186
	v_cvt_f32_ubyte2_e32 v220, v186
	v_cvt_f32_ubyte3_e32 v221, v186
	v_cvt_f32_ubyte0_e32 v222, v166
	v_cvt_f32_ubyte1_e32 v223, v166
	v_cvt_f32_ubyte2_e32 v242, v166
	v_cvt_f32_ubyte3_e32 v243, v166
	v_max_f32_e32 v206, s9, v206
	v_max_f32_e32 v207, s9, v207
	v_max_f32_e32 v220, s9, v220
	v_max_f32_e32 v221, s9, v221
	v_max_f32_e32 v222, s9, v222
	v_max_f32_e32 v223, s9, v223
	v_max_f32_e32 v242, s9, v242
	v_max_f32_e32 v243, s9, v243
	v_rcp_f32_e32 v206, v206
	v_rcp_f32_e32 v207, v207
	v_rcp_f32_e32 v220, v220
	v_rcp_f32_e32 v221, v221
	v_mul_f32_e32 v222, v206, v222
	v_mul_f32_e32 v223, v207, v223
	v_mul_f32_e32 v242, v220, v242
	v_mul_f32_e32 v243, v221, v243
	v_mul_f32_e32 v66, v222, v66
	v_mul_f32_e32 v67, v223, v67
	v_mul_f32_e32 v68, v242, v68
	v_mul_f32_e32 v69, v243, v69
	v_cvt_f32_ubyte0_e32 v206, v187
	v_cvt_f32_ubyte1_e32 v207, v187
	v_cvt_f32_ubyte2_e32 v220, v187
	v_cvt_f32_ubyte3_e32 v221, v187
	v_cvt_f32_ubyte0_e32 v222, v167
	v_cvt_f32_ubyte1_e32 v223, v167
	v_cvt_f32_ubyte2_e32 v242, v167
	v_cvt_f32_ubyte3_e32 v243, v167
	v_max_f32_e32 v206, s9, v206
	v_max_f32_e32 v207, s9, v207
	v_max_f32_e32 v220, s9, v220
	v_max_f32_e32 v221, s9, v221
	v_max_f32_e32 v222, s9, v222
	v_max_f32_e32 v223, s9, v223
	v_max_f32_e32 v242, s9, v242
	v_max_f32_e32 v243, s9, v243
	v_rcp_f32_e32 v206, v206
	v_rcp_f32_e32 v207, v207
	v_rcp_f32_e32 v220, v220
	v_rcp_f32_e32 v221, v221
	v_mul_f32_e32 v222, v206, v222
	v_mul_f32_e32 v223, v207, v223
	v_mul_f32_e32 v242, v220, v242
	v_mul_f32_e32 v243, v221, v243
	v_mul_f32_e32 v62, v222, v62
	v_mul_f32_e32 v63, v223, v63
	v_mul_f32_e32 v64, v242, v64
	v_mul_f32_e32 v65, v243, v65
	v_cvt_f32_ubyte0_e32 v206, v188
	v_cvt_f32_ubyte1_e32 v207, v188
	v_cvt_f32_ubyte2_e32 v220, v188
	v_cvt_f32_ubyte3_e32 v221, v188
	v_cvt_f32_ubyte0_e32 v222, v168
	v_cvt_f32_ubyte1_e32 v223, v168
	v_cvt_f32_ubyte2_e32 v242, v168
	v_cvt_f32_ubyte3_e32 v243, v168
	v_max_f32_e32 v206, s9, v206
	v_max_f32_e32 v207, s9, v207
	v_max_f32_e32 v220, s9, v220
	v_max_f32_e32 v221, s9, v221
	v_max_f32_e32 v222, s9, v222
	v_max_f32_e32 v223, s9, v223
	v_max_f32_e32 v242, s9, v242
	v_max_f32_e32 v243, s9, v243
	v_rcp_f32_e32 v206, v206
	v_rcp_f32_e32 v207, v207
	v_rcp_f32_e32 v220, v220
	v_rcp_f32_e32 v221, v221
	v_mul_f32_e32 v222, v206, v222
	v_mul_f32_e32 v223, v207, v223
	v_mul_f32_e32 v242, v220, v242
	v_mul_f32_e32 v243, v221, v243
	v_mul_f32_e32 v58, v222, v58
	v_mul_f32_e32 v59, v223, v59
	v_mul_f32_e32 v60, v242, v60
	v_mul_f32_e32 v61, v243, v61
	v_cvt_f32_ubyte0_e32 v206, v189
	v_cvt_f32_ubyte1_e32 v207, v189
	v_cvt_f32_ubyte2_e32 v220, v189
	v_cvt_f32_ubyte3_e32 v221, v189
	v_cvt_f32_ubyte0_e32 v222, v169
	v_cvt_f32_ubyte1_e32 v223, v169
	v_cvt_f32_ubyte2_e32 v242, v169
	v_cvt_f32_ubyte3_e32 v243, v169
	v_max_f32_e32 v206, s9, v206
	v_max_f32_e32 v207, s9, v207
	v_max_f32_e32 v220, s9, v220
	v_max_f32_e32 v221, s9, v221
	v_max_f32_e32 v222, s9, v222
	v_max_f32_e32 v223, s9, v223
	v_max_f32_e32 v242, s9, v242
	v_max_f32_e32 v243, s9, v243
	v_rcp_f32_e32 v206, v206
	v_rcp_f32_e32 v207, v207
	v_rcp_f32_e32 v220, v220
	v_rcp_f32_e32 v221, v221
	v_mul_f32_e32 v222, v206, v222
	v_mul_f32_e32 v223, v207, v223
	v_mul_f32_e32 v242, v220, v242
	v_mul_f32_e32 v243, v221, v243
	v_mul_f32_e32 v54, v222, v54
	v_mul_f32_e32 v55, v223, v55
	v_mul_f32_e32 v56, v242, v56
	v_mul_f32_e32 v57, v243, v57
	s_waitcnt vmcnt(4)
	v_cvt_f32_ubyte0_e32 v206, v208
	v_cvt_f32_ubyte1_e32 v207, v208
	v_cvt_f32_ubyte2_e32 v220, v208
	v_cvt_f32_ubyte3_e32 v221, v208
	v_cvt_f32_ubyte0_e32 v222, v170
	v_cvt_f32_ubyte1_e32 v223, v170
	v_cvt_f32_ubyte2_e32 v242, v170
	v_cvt_f32_ubyte3_e32 v243, v170
	v_max_f32_e32 v206, s9, v206
	v_max_f32_e32 v207, s9, v207
	v_max_f32_e32 v220, s9, v220
	v_max_f32_e32 v221, s9, v221
	v_max_f32_e32 v222, s9, v222
	v_max_f32_e32 v223, s9, v223
	v_max_f32_e32 v242, s9, v242
	v_max_f32_e32 v243, s9, v243
	v_rcp_f32_e32 v206, v206
	v_rcp_f32_e32 v207, v207
	v_rcp_f32_e32 v220, v220
	v_rcp_f32_e32 v221, v221
	v_mul_f32_e32 v222, v206, v222
	v_mul_f32_e32 v223, v207, v223
	v_mul_f32_e32 v242, v220, v242
	v_mul_f32_e32 v243, v221, v243
	v_mul_f32_e32 v50, v222, v50
	v_mul_f32_e32 v51, v223, v51
	v_mul_f32_e32 v52, v242, v52
	v_mul_f32_e32 v53, v243, v53
	v_cvt_f32_ubyte0_e32 v206, v209
	v_cvt_f32_ubyte1_e32 v207, v209
	v_cvt_f32_ubyte2_e32 v220, v209
	v_cvt_f32_ubyte3_e32 v221, v209
	v_cvt_f32_ubyte0_e32 v222, v171
	v_cvt_f32_ubyte1_e32 v223, v171
	v_cvt_f32_ubyte2_e32 v242, v171
	v_cvt_f32_ubyte3_e32 v243, v171
	v_max_f32_e32 v206, s9, v206
	v_max_f32_e32 v207, s9, v207
	v_max_f32_e32 v220, s9, v220
	v_max_f32_e32 v221, s9, v221
	v_max_f32_e32 v222, s9, v222
	v_max_f32_e32 v223, s9, v223
	v_max_f32_e32 v242, s9, v242
	v_max_f32_e32 v243, s9, v243
	v_rcp_f32_e32 v206, v206
	v_rcp_f32_e32 v207, v207
	v_rcp_f32_e32 v220, v220
	v_rcp_f32_e32 v221, v221
	v_mul_f32_e32 v222, v206, v222
	v_mul_f32_e32 v223, v207, v223
	v_mul_f32_e32 v242, v220, v242
	v_mul_f32_e32 v243, v221, v243
	v_mul_f32_e32 v46, v222, v46
	v_mul_f32_e32 v47, v223, v47
	v_mul_f32_e32 v48, v242, v48
	v_mul_f32_e32 v49, v243, v49
	v_cvt_f32_ubyte0_e32 v206, v210
	v_cvt_f32_ubyte1_e32 v207, v210
	v_cvt_f32_ubyte2_e32 v220, v210
	v_cvt_f32_ubyte3_e32 v221, v210
	v_cvt_f32_ubyte0_e32 v222, v172
	v_cvt_f32_ubyte1_e32 v223, v172
	v_cvt_f32_ubyte2_e32 v242, v172
	v_cvt_f32_ubyte3_e32 v243, v172
	v_max_f32_e32 v206, s9, v206
	v_max_f32_e32 v207, s9, v207
	v_max_f32_e32 v220, s9, v220
	v_max_f32_e32 v221, s9, v221
	v_max_f32_e32 v222, s9, v222
	v_max_f32_e32 v223, s9, v223
	v_max_f32_e32 v242, s9, v242
	v_max_f32_e32 v243, s9, v243
	v_rcp_f32_e32 v206, v206
	v_rcp_f32_e32 v207, v207
	v_rcp_f32_e32 v220, v220
	v_rcp_f32_e32 v221, v221
	v_mul_f32_e32 v222, v206, v222
	v_mul_f32_e32 v223, v207, v223
	v_mul_f32_e32 v242, v220, v242
	v_mul_f32_e32 v243, v221, v243
	v_mul_f32_e32 v42, v222, v42
	v_mul_f32_e32 v43, v223, v43
	v_mul_f32_e32 v44, v242, v44
	v_mul_f32_e32 v45, v243, v45
	v_cvt_f32_ubyte0_e32 v206, v211
	v_cvt_f32_ubyte1_e32 v207, v211
	v_cvt_f32_ubyte2_e32 v220, v211
	v_cvt_f32_ubyte3_e32 v221, v211
	v_cvt_f32_ubyte0_e32 v222, v173
	v_cvt_f32_ubyte1_e32 v223, v173
	v_cvt_f32_ubyte2_e32 v242, v173
	v_cvt_f32_ubyte3_e32 v243, v173
	v_max_f32_e32 v206, s9, v206
	v_max_f32_e32 v207, s9, v207
	v_max_f32_e32 v220, s9, v220
	v_max_f32_e32 v221, s9, v221
	v_max_f32_e32 v222, s9, v222
	v_max_f32_e32 v223, s9, v223
	v_max_f32_e32 v242, s9, v242
	v_max_f32_e32 v243, s9, v243
	v_rcp_f32_e32 v206, v206
	v_rcp_f32_e32 v207, v207
	v_rcp_f32_e32 v220, v220
	v_rcp_f32_e32 v221, v221
	v_mul_f32_e32 v222, v206, v222
	v_mul_f32_e32 v223, v207, v223
	v_mul_f32_e32 v242, v220, v242
	v_mul_f32_e32 v243, v221, v243
	v_mul_f32_e32 v38, v222, v38
	v_mul_f32_e32 v39, v223, v39
	v_mul_f32_e32 v40, v242, v40
	v_mul_f32_e32 v41, v243, v41
	s_waitcnt vmcnt(2)
; template <class Epi, class Sched>
; __device__ __forceinline__ void gemm_phase(const int TID, LAS unsigned char* lds, const int lda, const int ldb, const Sched& S, const Epi& E) {
;     ...
;         cur = nxt; cA = nA; cB = nB; ++ui;
	v_cvt_f32_ubyte0_e32 v206, v212
	v_cvt_f32_ubyte1_e32 v207, v212
	v_cvt_f32_ubyte2_e32 v220, v212
	v_cvt_f32_ubyte3_e32 v221, v212
	v_cvt_f32_ubyte0_e32 v222, v174
	v_cvt_f32_ubyte1_e32 v223, v174
	v_cvt_f32_ubyte2_e32 v242, v174
	v_cvt_f32_ubyte3_e32 v243, v174
	v_max_f32_e32 v206, s9, v206
	v_max_f32_e32 v207, s9, v207
	v_max_f32_e32 v220, s9, v220
	v_max_f32_e32 v221, s9, v221
	v_max_f32_e32 v222, s9, v222
	v_max_f32_e32 v223, s9, v223
	v_max_f32_e32 v242, s9, v242
	v_max_f32_e32 v243, s9, v243
	v_rcp_f32_e32 v206, v206
	v_rcp_f32_e32 v207, v207
	v_rcp_f32_e32 v220, v220
	v_rcp_f32_e32 v221, v221
	v_mul_f32_e32 v222, v206, v222
	v_mul_f32_e32 v223, v207, v223
	v_mul_f32_e32 v242, v220, v242
	v_mul_f32_e32 v243, v221, v243
	v_mul_f32_e32 v34, v222, v34
	v_mul_f32_e32 v35, v223, v35
	v_mul_f32_e32 v36, v242, v36
	v_mul_f32_e32 v37, v243, v37
	v_cvt_f32_ubyte0_e32 v206, v213
	v_cvt_f32_ubyte1_e32 v207, v213
	v_cvt_f32_ubyte2_e32 v220, v213
	v_cvt_f32_ubyte3_e32 v221, v213
	v_cvt_f32_ubyte0_e32 v222, v175
	v_cvt_f32_ubyte1_e32 v223, v175
	v_cvt_f32_ubyte2_e32 v242, v175
	v_cvt_f32_ubyte3_e32 v243, v175
	v_max_f32_e32 v206, s9, v206
	v_max_f32_e32 v207, s9, v207
	v_max_f32_e32 v220, s9, v220
	v_max_f32_e32 v221, s9, v221
	v_max_f32_e32 v222, s9, v222
	v_max_f32_e32 v223, s9, v223
	v_max_f32_e32 v242, s9, v242
	v_max_f32_e32 v243, s9, v243
	v_rcp_f32_e32 v206, v206
	v_rcp_f32_e32 v207, v207
	v_rcp_f32_e32 v220, v220
	v_rcp_f32_e32 v221, v221
	v_mul_f32_e32 v222, v206, v222
	v_mul_f32_e32 v223, v207, v223
	v_mul_f32_e32 v242, v220, v242
	v_mul_f32_e32 v243, v221, v243
	v_mul_f32_e32 v30, v222, v30
	v_mul_f32_e32 v31, v223, v31
	v_mul_f32_e32 v32, v242, v32
	v_mul_f32_e32 v33, v243, v33
	v_cvt_f32_ubyte0_e32 v206, v214
	v_cvt_f32_ubyte1_e32 v207, v214
	v_cvt_f32_ubyte2_e32 v220, v214
	v_cvt_f32_ubyte3_e32 v221, v214
	v_cvt_f32_ubyte0_e32 v222, v176
	v_cvt_f32_ubyte1_e32 v223, v176
	v_cvt_f32_ubyte2_e32 v242, v176
	v_cvt_f32_ubyte3_e32 v243, v176
	v_max_f32_e32 v206, s9, v206
	v_max_f32_e32 v207, s9, v207
	v_max_f32_e32 v220, s9, v220
	v_max_f32_e32 v221, s9, v221
	v_max_f32_e32 v222, s9, v222
	v_max_f32_e32 v223, s9, v223
	v_max_f32_e32 v242, s9, v242
	v_max_f32_e32 v243, s9, v243
	v_rcp_f32_e32 v206, v206
	v_rcp_f32_e32 v207, v207
	v_rcp_f32_e32 v220, v220
	v_rcp_f32_e32 v221, v221
	v_mul_f32_e32 v222, v206, v222
	v_mul_f32_e32 v223, v207, v223
	v_mul_f32_e32 v242, v220, v242
	v_mul_f32_e32 v243, v221, v243
	v_mul_f32_e32 v26, v222, v26
	v_mul_f32_e32 v27, v223, v27
	v_mul_f32_e32 v28, v242, v28
	v_mul_f32_e32 v29, v243, v29
	v_cvt_f32_ubyte0_e32 v206, v215
	v_cvt_f32_ubyte1_e32 v207, v215
	v_cvt_f32_ubyte2_e32 v220, v215
	v_cvt_f32_ubyte3_e32 v221, v215
	v_cvt_f32_ubyte0_e32 v222, v177
	v_cvt_f32_ubyte1_e32 v223, v177
	v_cvt_f32_ubyte2_e32 v242, v177
	v_cvt_f32_ubyte3_e32 v243, v177
	v_max_f32_e32 v206, s9, v206
	v_max_f32_e32 v207, s9, v207
	v_max_f32_e32 v220, s9, v220
	v_max_f32_e32 v221, s9, v221
	v_max_f32_e32 v222, s9, v222
	v_max_f32_e32 v223, s9, v223
	v_max_f32_e32 v242, s9, v242
	v_max_f32_e32 v243, s9, v243
	v_rcp_f32_e32 v206, v206
	v_rcp_f32_e32 v207, v207
	v_rcp_f32_e32 v220, v220
	v_rcp_f32_e32 v221, v221
	v_mul_f32_e32 v222, v206, v222
	v_mul_f32_e32 v223, v207, v223
	v_mul_f32_e32 v242, v220, v242
	v_mul_f32_e32 v243, v221, v243
	v_mul_f32_e32 v22, v222, v22
	v_mul_f32_e32 v23, v223, v23
	v_mul_f32_e32 v24, v242, v24
	v_mul_f32_e32 v25, v243, v25
	s_waitcnt vmcnt(0)
	v_cvt_f32_ubyte0_e32 v206, v216
	v_cvt_f32_ubyte1_e32 v207, v216
	v_cvt_f32_ubyte2_e32 v220, v216
	v_cvt_f32_ubyte3_e32 v221, v216
	v_cvt_f32_ubyte0_e32 v222, v178
	v_cvt_f32_ubyte1_e32 v223, v178
	v_cvt_f32_ubyte2_e32 v242, v178
	v_cvt_f32_ubyte3_e32 v243, v178
	v_max_f32_e32 v206, s9, v206
	v_max_f32_e32 v207, s9, v207
	v_max_f32_e32 v220, s9, v220
	v_max_f32_e32 v221, s9, v221
	v_max_f32_e32 v222, s9, v222
	v_max_f32_e32 v223, s9, v223
	v_max_f32_e32 v242, s9, v242
	v_max_f32_e32 v243, s9, v243
	v_rcp_f32_e32 v206, v206
	v_rcp_f32_e32 v207, v207
	v_rcp_f32_e32 v220, v220
	v_rcp_f32_e32 v221, v221
	v_mul_f32_e32 v222, v206, v222
	v_mul_f32_e32 v223, v207, v223
	v_mul_f32_e32 v242, v220, v242
	v_mul_f32_e32 v243, v221, v243
	v_mul_f32_e32 v18, v222, v18
	v_mul_f32_e32 v19, v223, v19
	v_mul_f32_e32 v20, v242, v20
	v_mul_f32_e32 v21, v243, v21
	v_cvt_f32_ubyte0_e32 v206, v217
	v_cvt_f32_ubyte1_e32 v207, v217
	v_cvt_f32_ubyte2_e32 v220, v217
	v_cvt_f32_ubyte3_e32 v221, v217
	v_cvt_f32_ubyte0_e32 v222, v179
	v_cvt_f32_ubyte1_e32 v223, v179
	v_cvt_f32_ubyte2_e32 v242, v179
	v_cvt_f32_ubyte3_e32 v243, v179
	v_max_f32_e32 v206, s9, v206
	v_max_f32_e32 v207, s9, v207
	v_max_f32_e32 v220, s9, v220
	v_max_f32_e32 v221, s9, v221
	v_max_f32_e32 v222, s9, v222
	v_max_f32_e32 v223, s9, v223
	v_max_f32_e32 v242, s9, v242
	v_max_f32_e32 v243, s9, v243
	v_rcp_f32_e32 v206, v206
	v_rcp_f32_e32 v207, v207
	v_rcp_f32_e32 v220, v220
	v_rcp_f32_e32 v221, v221
	v_mul_f32_e32 v222, v206, v222
	v_mul_f32_e32 v223, v207, v223
	v_mul_f32_e32 v242, v220, v242
	v_mul_f32_e32 v243, v221, v243
	v_mul_f32_e32 v8, v222, v8
	v_mul_f32_e32 v9, v223, v9
	v_mul_f32_e32 v10, v242, v10
	v_mul_f32_e32 v11, v243, v11
	v_cvt_f32_ubyte0_e32 v206, v218
	v_cvt_f32_ubyte1_e32 v207, v218
	v_cvt_f32_ubyte2_e32 v220, v218
	v_cvt_f32_ubyte3_e32 v221, v218
	v_cvt_f32_ubyte0_e32 v222, v180
	v_cvt_f32_ubyte1_e32 v223, v180
	v_cvt_f32_ubyte2_e32 v242, v180
	v_cvt_f32_ubyte3_e32 v243, v180
	v_max_f32_e32 v206, s9, v206
	v_max_f32_e32 v207, s9, v207
	v_max_f32_e32 v220, s9, v220
	v_max_f32_e32 v221, s9, v221
	v_max_f32_e32 v222, s9, v222
	v_max_f32_e32 v223, s9, v223
	v_max_f32_e32 v242, s9, v242
	v_max_f32_e32 v243, s9, v243
	v_rcp_f32_e32 v206, v206
	v_rcp_f32_e32 v207, v207
	v_rcp_f32_e32 v220, v220
	v_rcp_f32_e32 v221, v221
	v_mul_f32_e32 v222, v206, v222
	v_mul_f32_e32 v223, v207, v223
	v_mul_f32_e32 v242, v220, v242
	v_mul_f32_e32 v243, v221, v243
	v_mul_f32_e32 v4, v222, v4
	v_mul_f32_e32 v5, v223, v5
	v_mul_f32_e32 v6, v242, v6
	v_mul_f32_e32 v7, v243, v7
	v_cvt_f32_ubyte0_e32 v206, v219
	v_cvt_f32_ubyte1_e32 v207, v219
	v_cvt_f32_ubyte2_e32 v220, v219
	v_cvt_f32_ubyte3_e32 v221, v219
	v_cvt_f32_ubyte0_e32 v222, v181
	v_cvt_f32_ubyte1_e32 v223, v181
	v_cvt_f32_ubyte2_e32 v242, v181
	v_cvt_f32_ubyte3_e32 v243, v181
	v_max_f32_e32 v206, s9, v206
	v_max_f32_e32 v207, s9, v207
	v_max_f32_e32 v220, s9, v220
	v_max_f32_e32 v221, s9, v221
	v_max_f32_e32 v222, s9, v222
	v_max_f32_e32 v223, s9, v223
	v_max_f32_e32 v242, s9, v242
	v_max_f32_e32 v243, s9, v243
	v_rcp_f32_e32 v206, v206
	v_rcp_f32_e32 v207, v207
	v_rcp_f32_e32 v220, v220
	v_rcp_f32_e32 v221, v221
	v_mul_f32_e32 v222, v206, v222
	v_mul_f32_e32 v223, v207, v223
	v_mul_f32_e32 v242, v220, v242
	v_mul_f32_e32 v243, v221, v243
	v_mul_f32_e32 v0, v222, v0
	v_mul_f32_e32 v1, v223, v1
	v_mul_f32_e32 v2, v242, v2
	v_mul_f32_e32 v3, v243, v3
	s_mov_b32 s68, s66
	s_mov_b32 s41, s64
	s_mov_b32 s67, s44
	s_mov_b32 s40, s46
	s_mov_b64 s[54:55], s[50:51]
	s_mov_b64 s[52:53], s[48:49]
	s_branch .LBB0_233
